# v5 plus: second LDS-DMA of each load phase gets its own address register pair (no VALU wait on the first DMA's address read)
# baseline (speedup 1.0000x reference)
; #define PG8_STAGE(bufoff, gbase, voff) do { _Pragma("unroll") for (int _i = 0; _i < 2; ++_i) \
;         __builtin_amdgcn_global_load_lds((const unsigned*)((const char*)(gbase) + (voff)[_i]), (LAS unsigned*)(lds + (bufoff) + ldsw + _i * 8192), 16, 0, 0); } while (0)
; #define PG8_LDA(dst, b, h) do { _Pragma("unroll") for (int m = 0; m < 4; ++m) _Pragma("unroll") for (int k = 0; k < 2; ++k) dst[m][k] = *(const LAS bf16x8*)(lds + PG8_SA(b, h) + aoff + m * 2048 + k * 1024); } while (0)
; #define PG8_LDB(dst, b, h) do { _Pragma("unroll") for (int n = 0; n < 2; ++n) _Pragma("unroll") for (int k = 0; k < 2; ++k) dst[n][k] = *(const LAS bf16x8*)(lds + PG8_SB(b, h) + boff + n * 2048 + k * 1024); } while (0)
; #define PG8_MMA(ai, bj, At, Bt) do { __builtin_amdgcn_s_setprio(1); _Pragma("unroll") for (int m = 0; m < 4; ++m) _Pragma("unroll") for (int n = 0; n < 2; ++n) _Pragma("unroll") for (int k = 0; k < 2; ++k) \
;         acc[ai][bj][m][n] = __builtin_amdgcn_mfma_f32_16x16x32_bf16(Bt[n][k], At[m][k], acc[ai][bj][m][n], 0, 0, 0); __builtin_amdgcn_s_setprio(0); } while (0)
; #define PG8_WAIT_L(n) asm volatile("s_waitcnt lgkmcnt(" #n ")" ::: "memory")
; #define PG8_BAR __builtin_amdgcn_s_barrier()
; #define PG8_SCHED __builtin_amdgcn_sched_barrier(0)
; template <class Epi, class Sched>
; __device__ __forceinline__ void gemm_phase(LAS unsigned char* lds, const Gemm g, const Sched& S, const Epi& E) {
;     ...
;         for (int t = 0; t < nt; t += 2) {
;             const bool last = (t == nt - 2);
;             const char* a1 = cA + (size_t)(t + 1) * kstep;
;             const char* a2 = last ? nA : cA + (size_t)(t + 2) * kstep; const char* b2 = last ? nB : cB + (size_t)(t + 2) * kstep;
;             const char* a3 = a2 + kstep; const char* b3 = b2 + kstep;
;             PG8_LDB(B0, 0, 0); PG8_SCHED; PG8_LDA(At, 0, 0); PG8_STAGE(PG8_SA(1, 1), a1 + hstep, voffA);
;             PG8_WAIT_L(8); PG8_BAR; PG8_WAIT_L(0); PG8_MMA(0, 0, At, B0); PG8_BAR; PG8_SCHED;
;             PG8_LDB(B1, 0, 1); PG8_STAGE(PG8_SB(0, 0), b2, voffB);
;             PG8_BAR; PG8_WAIT_L(0); PG8_MMA(0, 1, At, B1); PG8_BAR;
;             PG8_LDA(At, 0, 1); PG8_STAGE(PG8_SA(0, 0), a2, voffA);
;             PG8_BAR; PG8_WAIT_L(0); PG8_MMA(1, 0, At, B0); PG8_BAR; PG8_SCHED;
.LBB0_165:
	s_add_u32 s24, s38, 0xfffc0080
	s_addc_u32 s25, s39, -1
	s_add_i32 vcc_hi, 0, 0x10000
	v_add_u32_e32 v166, vcc_hi, v167
	s_cmp_eq_u32 s50, 12
	s_cselect_b32 s61, s34, s25
	s_cselect_b32 s60, s45, s24
	s_cselect_b32 s49, s43, s35
	s_cselect_b32 s48, s79, vcc_lo
	v_lshl_add_u64 v[222:223], s[38:39], 0, v[140:141]
	s_add_i32 m0, s93, 0xc000
	ds_read_b128 v[190:193], v169
	ds_read_b128 v[194:197], v169 offset:1024
	ds_read_b128 v[198:201], v169 offset:2048
	ds_read_b128 v[202:205], v169 offset:3072
	ds_read_b128 v[206:209], v169 offset:4096
	ds_read_b128 v[210:213], v169 offset:5120
	ds_read_b128 v[214:217], v169 offset:6144
	ds_read_b128 v[218:221], v169 offset:7168
	global_load_lds_dwordx4 v[222:223], off
	v_lshl_add_u64 v[250:251], s[38:39], 0, v[138:139]
	s_add_i32 m0, s93, 0xe000
	s_nop 0
	global_load_lds_dwordx4 v[250:251], off
	s_waitcnt lgkmcnt(8)
	s_barrier
	s_waitcnt lgkmcnt(0)
	s_setprio 1
	s_waitcnt lgkmcnt(0)
	v_mfma_f32_16x16x32_bf16 v[126:129], v[142:145], v[190:193], v[126:129]
	v_mfma_f32_16x16x32_bf16 v[126:129], v[162:165], v[194:197], v[126:129]
	v_mfma_f32_16x16x32_bf16 v[122:125], v[182:185], v[190:193], v[122:125]
	v_mfma_f32_16x16x32_bf16 v[122:125], v[186:189], v[194:197], v[122:125]
	v_mfma_f32_16x16x32_bf16 v[110:113], v[142:145], v[198:201], v[110:113]
	v_mfma_f32_16x16x32_bf16 v[110:113], v[162:165], v[202:205], v[110:113]
	v_mfma_f32_16x16x32_bf16 v[106:109], v[182:185], v[198:201], v[106:109]
	v_mfma_f32_16x16x32_bf16 v[106:109], v[186:189], v[202:205], v[106:109]
	v_mfma_f32_16x16x32_bf16 v[94:97], v[142:145], v[206:209], v[94:97]
	v_mfma_f32_16x16x32_bf16 v[94:97], v[162:165], v[210:213], v[94:97]
	v_mfma_f32_16x16x32_bf16 v[90:93], v[182:185], v[206:209], v[90:93]
	v_mfma_f32_16x16x32_bf16 v[90:93], v[186:189], v[210:213], v[90:93]
	v_mfma_f32_16x16x32_bf16 v[78:81], v[142:145], v[214:217], v[78:81]
	v_mfma_f32_16x16x32_bf16 v[78:81], v[162:165], v[218:221], v[78:81]
	v_mfma_f32_16x16x32_bf16 v[74:77], v[182:185], v[214:217], v[74:77]
	s_barrier
	v_mfma_f32_16x16x32_bf16 v[74:77], v[186:189], v[218:221], v[74:77]
	s_setprio 0
	s_add_i32 s51, 0, 0x14000
	s_add_i32 s24, vcc_hi, s86
	v_add_u32_e32 v166, s51, v167
	v_lshl_add_u64 v[238:239], s[48:49], 0, v[134:135]
	s_mov_b32 m0, s24
	ds_read_b128 v[222:225], v166
	ds_read_b128 v[226:229], v166 offset:1024
	ds_read_b128 v[230:233], v166 offset:2048
	ds_read_b128 v[234:237], v166 offset:3072
	global_load_lds_dwordx4 v[238:239], off
	v_lshl_add_u64 v[240:241], s[48:49], 0, v[130:131]
	s_add_i32 m0, s24, 0x2000
	s_nop 0
	global_load_lds_dwordx4 v[240:241], off
	s_barrier
	s_waitcnt lgkmcnt(0)
	s_setprio 1
	s_waitcnt lgkmcnt(0)
	v_mfma_f32_16x16x32_bf16 v[118:121], v[222:225], v[190:193], v[118:121]
	v_mfma_f32_16x16x32_bf16 v[118:121], v[226:229], v[194:197], v[118:121]
	v_mfma_f32_16x16x32_bf16 v[114:117], v[230:233], v[190:193], v[114:117]
	v_mfma_f32_16x16x32_bf16 v[114:117], v[234:237], v[194:197], v[114:117]
	v_mfma_f32_16x16x32_bf16 v[102:105], v[222:225], v[198:201], v[102:105]
	v_mfma_f32_16x16x32_bf16 v[102:105], v[226:229], v[202:205], v[102:105]
	v_mfma_f32_16x16x32_bf16 v[98:101], v[230:233], v[198:201], v[98:101]
	v_mfma_f32_16x16x32_bf16 v[98:101], v[234:237], v[202:205], v[98:101]
	v_mfma_f32_16x16x32_bf16 v[86:89], v[222:225], v[206:209], v[86:89]
	v_mfma_f32_16x16x32_bf16 v[86:89], v[226:229], v[210:213], v[86:89]
	v_mfma_f32_16x16x32_bf16 v[82:85], v[230:233], v[206:209], v[82:85]
	v_mfma_f32_16x16x32_bf16 v[82:85], v[234:237], v[210:213], v[82:85]
	v_mfma_f32_16x16x32_bf16 v[70:73], v[222:225], v[214:217], v[70:73]
	v_mfma_f32_16x16x32_bf16 v[70:73], v[226:229], v[218:221], v[70:73]
	v_mfma_f32_16x16x32_bf16 v[66:69], v[230:233], v[214:217], v[66:69]
	s_barrier
	v_mfma_f32_16x16x32_bf16 v[66:69], v[234:237], v[218:221], v[66:69]
	s_setprio 0
	s_mov_b32 m0, s93
	v_lshl_add_u64 v[242:243], s[60:61], 0, v[136:137]
	ds_read_b128 v[190:193], v169 offset:16384
	ds_read_b128 v[194:197], v169 offset:17408
	ds_read_b128 v[198:201], v169 offset:18432
	ds_read_b128 v[202:205], v169 offset:19456
	ds_read_b128 v[206:209], v169 offset:20480
	ds_read_b128 v[210:213], v169 offset:21504
	ds_read_b128 v[214:217], v169 offset:22528
	ds_read_b128 v[218:221], v169 offset:23552
	global_load_lds_dwordx4 v[242:243], off
	v_lshl_add_u64 v[244:245], s[60:61], 0, v[132:133]
	s_mov_b32 m0, s98
	s_nop 0
	global_load_lds_dwordx4 v[244:245], off
	s_waitcnt vmcnt(8)
	s_barrier
	s_waitcnt lgkmcnt(0)
	s_setprio 1
	s_waitcnt lgkmcnt(0)
	v_mfma_f32_16x16x32_bf16 v[62:65], v[142:145], v[190:193], v[62:65]
	v_mfma_f32_16x16x32_bf16 v[62:65], v[162:165], v[194:197], v[62:65]
	v_mfma_f32_16x16x32_bf16 v[58:61], v[182:185], v[190:193], v[58:61]
	v_mfma_f32_16x16x32_bf16 v[58:61], v[186:189], v[194:197], v[58:61]
	v_mfma_f32_16x16x32_bf16 v[46:49], v[142:145], v[198:201], v[46:49]
	v_mfma_f32_16x16x32_bf16 v[46:49], v[162:165], v[202:205], v[46:49]
	v_mfma_f32_16x16x32_bf16 v[42:45], v[182:185], v[198:201], v[42:45]
	v_mfma_f32_16x16x32_bf16 v[42:45], v[186:189], v[202:205], v[42:45]
	v_mfma_f32_16x16x32_bf16 v[30:33], v[142:145], v[206:209], v[30:33]
	v_mfma_f32_16x16x32_bf16 v[30:33], v[162:165], v[210:213], v[30:33]
	v_mfma_f32_16x16x32_bf16 v[26:29], v[182:185], v[206:209], v[26:29]
	v_mfma_f32_16x16x32_bf16 v[26:29], v[186:189], v[210:213], v[26:29]
	v_mfma_f32_16x16x32_bf16 v[14:17], v[142:145], v[214:217], v[14:17]
	v_mfma_f32_16x16x32_bf16 v[14:17], v[162:165], v[218:221], v[14:17]
	v_mfma_f32_16x16x32_bf16 v[10:13], v[182:185], v[214:217], v[10:13]
	s_barrier
; #define PG8_STAGE(bufoff, gbase, voff) do { _Pragma("unroll") for (int _i = 0; _i < 2; ++_i) \
;         __builtin_amdgcn_global_load_lds((const unsigned*)((const char*)(gbase) + (voff)[_i]), (LAS unsigned*)(lds + (bufoff) + ldsw + _i * 8192), 16, 0, 0); } while (0)
; #define PG8_LDA(dst, b, h) do { _Pragma("unroll") for (int m = 0; m < 4; ++m) _Pragma("unroll") for (int k = 0; k < 2; ++k) dst[m][k] = *(const LAS bf16x8*)(lds + PG8_SA(b, h) + aoff + m * 2048 + k * 1024); } while (0)
; #define PG8_LDB(dst, b, h) do { _Pragma("unroll") for (int n = 0; n < 2; ++n) _Pragma("unroll") for (int k = 0; k < 2; ++k) dst[n][k] = *(const LAS bf16x8*)(lds + PG8_SB(b, h) + boff + n * 2048 + k * 1024); } while (0)
; #define PG8_MMA(ai, bj, At, Bt) do { __builtin_amdgcn_s_setprio(1); _Pragma("unroll") for (int m = 0; m < 4; ++m) _Pragma("unroll") for (int n = 0; n < 2; ++n) _Pragma("unroll") for (int k = 0; k < 2; ++k) \
;         acc[ai][bj][m][n] = __builtin_amdgcn_mfma_f32_16x16x32_bf16(Bt[n][k], At[m][k], acc[ai][bj][m][n], 0, 0, 0); __builtin_amdgcn_s_setprio(0); } while (0)
; #define PG8_WAIT_V(n) asm volatile("s_waitcnt vmcnt(" #n ")" ::: "memory")
; #define PG8_WAIT_L(n) asm volatile("s_waitcnt lgkmcnt(" #n ")" ::: "memory")
; #define PG8_BAR __builtin_amdgcn_s_barrier()
; #define PG8_SCHED __builtin_amdgcn_sched_barrier(0)
; template <class Epi, class Sched>
; __device__ __forceinline__ void gemm_phase(LAS unsigned char* lds, const Gemm g, const Sched& S, const Epi& E) {
;     ...
;             PG8_STAGE(PG8_SB(0, 1), b2 + hstep, voffB);
;             PG8_WAIT_V(6); PG8_BAR; PG8_MMA(1, 1, At, B1); PG8_BAR;
;             PG8_LDB(B0, 1, 0); PG8_SCHED; PG8_LDA(At, 1, 0); PG8_STAGE(PG8_SA(0, 1), a2 + hstep, voffA);
;             PG8_WAIT_L(8); PG8_BAR; PG8_WAIT_L(0); PG8_MMA(0, 0, At, B0); PG8_BAR; PG8_SCHED;
;             PG8_LDB(B1, 1, 1); PG8_STAGE(PG8_SB(1, 0), b3, voffB);
	v_mfma_f32_16x16x32_bf16 v[10:13], v[186:189], v[218:221], v[10:13]
	s_setprio 0
	s_add_u32 s24, s48, 0x40000
	s_addc_u32 s25, s49, 0
	s_add_i32 s51, s51, s86
	v_lshl_add_u64 v[142:143], s[24:25], 0, v[134:135]
	s_mov_b32 m0, s51
	s_nop 0
	global_load_lds_dwordx4 v[142:143], off
	v_lshl_add_u64 v[250:251], s[24:25], 0, v[130:131]
	s_add_i32 m0, s51, 0x2000
	s_nop 0
	global_load_lds_dwordx4 v[250:251], off
	s_waitcnt vmcnt(6)
	s_barrier
	s_setprio 1
	v_add_u32_e32 v249, 0x18000, v167
	v_mfma_f32_16x16x32_bf16 v[54:57], v[222:225], v[190:193], v[54:57]
	v_mfma_f32_16x16x32_bf16 v[54:57], v[226:229], v[194:197], v[54:57]
	ds_read_b128 v[142:145], v249
	v_mfma_f32_16x16x32_bf16 v[50:53], v[230:233], v[190:193], v[50:53]
	v_mfma_f32_16x16x32_bf16 v[50:53], v[234:237], v[194:197], v[50:53]
	v_mfma_f32_16x16x32_bf16 v[38:41], v[222:225], v[198:201], v[38:41]
	v_mfma_f32_16x16x32_bf16 v[38:41], v[226:229], v[202:205], v[38:41]
	ds_read_b128 v[162:165], v249 offset:1024
	v_mfma_f32_16x16x32_bf16 v[34:37], v[230:233], v[198:201], v[34:37]
	v_mfma_f32_16x16x32_bf16 v[34:37], v[234:237], v[202:205], v[34:37]
	v_mfma_f32_16x16x32_bf16 v[22:25], v[222:225], v[206:209], v[22:25]
	v_mfma_f32_16x16x32_bf16 v[22:25], v[226:229], v[210:213], v[22:25]
	ds_read_b128 v[182:185], v249 offset:2048
	v_mfma_f32_16x16x32_bf16 v[18:21], v[230:233], v[206:209], v[18:21]
	v_mfma_f32_16x16x32_bf16 v[18:21], v[234:237], v[210:213], v[18:21]
	v_mfma_f32_16x16x32_bf16 v[6:9], v[222:225], v[214:217], v[6:9]
	v_mfma_f32_16x16x32_bf16 v[6:9], v[226:229], v[218:221], v[6:9]
	ds_read_b128 v[186:189], v249 offset:3072
	v_mfma_f32_16x16x32_bf16 v[2:5], v[230:233], v[214:217], v[2:5]
	s_barrier
	v_mfma_f32_16x16x32_bf16 v[2:5], v[234:237], v[218:221], v[2:5]
	s_setprio 0
	s_add_i32 s51, 0, 0x18000
	v_add_u32_e32 v166, s51, v167
	s_add_u32 s24, s60, 0x40000
	s_addc_u32 s25, s61, 0
	s_mov_b32 m0, s99
	v_lshl_add_u64 v[222:223], s[24:25], 0, v[136:137]
	ds_read_b128 v[190:193], v169 offset:32768
	ds_read_b128 v[194:197], v169 offset:33792
	ds_read_b128 v[198:201], v169 offset:34816
	ds_read_b128 v[202:205], v169 offset:35840
	ds_read_b128 v[206:209], v169 offset:36864
	ds_read_b128 v[210:213], v169 offset:37888
	ds_read_b128 v[214:217], v169 offset:38912
	ds_read_b128 v[218:221], v169 offset:39936
	global_load_lds_dwordx4 v[222:223], off
	v_lshl_add_u64 v[250:251], s[24:25], 0, v[132:133]
	s_mov_b32 m0, s94
	s_nop 0
	global_load_lds_dwordx4 v[250:251], off
	s_waitcnt lgkmcnt(8)
	s_barrier
	s_waitcnt lgkmcnt(0)
	s_setprio 1
	s_waitcnt lgkmcnt(0)
	v_mfma_f32_16x16x32_bf16 v[126:129], v[142:145], v[190:193], v[126:129]
	v_mfma_f32_16x16x32_bf16 v[126:129], v[162:165], v[194:197], v[126:129]
	v_mfma_f32_16x16x32_bf16 v[122:125], v[182:185], v[190:193], v[122:125]
	v_mfma_f32_16x16x32_bf16 v[122:125], v[186:189], v[194:197], v[122:125]
	v_mfma_f32_16x16x32_bf16 v[110:113], v[142:145], v[198:201], v[110:113]
	v_mfma_f32_16x16x32_bf16 v[110:113], v[162:165], v[202:205], v[110:113]
	v_mfma_f32_16x16x32_bf16 v[106:109], v[182:185], v[198:201], v[106:109]
	v_mfma_f32_16x16x32_bf16 v[106:109], v[186:189], v[202:205], v[106:109]
	v_mfma_f32_16x16x32_bf16 v[94:97], v[142:145], v[206:209], v[94:97]
	v_mfma_f32_16x16x32_bf16 v[94:97], v[162:165], v[210:213], v[94:97]
	v_mfma_f32_16x16x32_bf16 v[90:93], v[182:185], v[206:209], v[90:93]
	v_mfma_f32_16x16x32_bf16 v[90:93], v[186:189], v[210:213], v[90:93]
	v_mfma_f32_16x16x32_bf16 v[78:81], v[142:145], v[214:217], v[78:81]
	v_mfma_f32_16x16x32_bf16 v[78:81], v[162:165], v[218:221], v[78:81]
	v_mfma_f32_16x16x32_bf16 v[74:77], v[182:185], v[214:217], v[74:77]
	s_barrier
	v_mfma_f32_16x16x32_bf16 v[74:77], v[186:189], v[218:221], v[74:77]
	s_setprio 0
	s_add_i32 s60, 0, 0x1c000
	s_add_i32 s24, s51, s86
	v_add_u32_e32 v166, s60, v167
	v_lshl_add_u64 v[238:239], v[238:239], 0, s[12:13]
	s_mov_b32 m0, s24
	ds_read_b128 v[222:225], v166
	ds_read_b128 v[226:229], v166 offset:1024
	ds_read_b128 v[230:233], v166 offset:2048
	ds_read_b128 v[234:237], v166 offset:3072
	global_load_lds_dwordx4 v[238:239], off
	v_lshl_add_u64 v[250:251], v[240:241], 0, s[12:13]
	s_add_i32 m0, s24, 0x2000
	s_nop 0
	global_load_lds_dwordx4 v[250:251], off
	s_barrier
; #define PG8_STAGE(bufoff, gbase, voff) do { _Pragma("unroll") for (int _i = 0; _i < 2; ++_i) \
;         __builtin_amdgcn_global_load_lds((const unsigned*)((const char*)(gbase) + (voff)[_i]), (LAS unsigned*)(lds + (bufoff) + ldsw + _i * 8192), 16, 0, 0); } while (0)
; #define PG8_LDA(dst, b, h) do { _Pragma("unroll") for (int m = 0; m < 4; ++m) _Pragma("unroll") for (int k = 0; k < 2; ++k) dst[m][k] = *(const LAS bf16x8*)(lds + PG8_SA(b, h) + aoff + m * 2048 + k * 1024); } while (0)
; #define PG8_MMA(ai, bj, At, Bt) do { __builtin_amdgcn_s_setprio(1); _Pragma("unroll") for (int m = 0; m < 4; ++m) _Pragma("unroll") for (int n = 0; n < 2; ++n) _Pragma("unroll") for (int k = 0; k < 2; ++k) \
;         acc[ai][bj][m][n] = __builtin_amdgcn_mfma_f32_16x16x32_bf16(Bt[n][k], At[m][k], acc[ai][bj][m][n], 0, 0, 0); __builtin_amdgcn_s_setprio(0); } while (0)
; #define PG8_WAIT_V(n) asm volatile("s_waitcnt vmcnt(" #n ")" ::: "memory")
; #define PG8_WAIT_L(n) asm volatile("s_waitcnt lgkmcnt(" #n ")" ::: "memory")
; #define PG8_BAR __builtin_amdgcn_s_barrier()
; #define PG8_SCHED __builtin_amdgcn_sched_barrier(0)
; template <class Epi, class Sched>
; __device__ __forceinline__ void gemm_phase(LAS unsigned char* lds, const Gemm g, const Sched& S, const Epi& E) {
;     ...
;             PG8_BAR; PG8_WAIT_L(0); PG8_MMA(0, 1, At, B1); PG8_BAR;
;             PG8_LDA(At, 1, 1); PG8_STAGE(PG8_SA(1, 0), a3, voffA);
;             PG8_BAR; PG8_WAIT_L(0); PG8_MMA(1, 0, At, B0); PG8_BAR; PG8_SCHED;
;             PG8_STAGE(PG8_SB(1, 1), b3 + hstep, voffB);
;             PG8_WAIT_V(6); PG8_BAR; PG8_MMA(1, 1, At, B1); PG8_BAR;
;         }
;         if (wr == 0) PG8_BAR;
	s_waitcnt lgkmcnt(0)
	s_setprio 1
	s_waitcnt lgkmcnt(0)
	v_mfma_f32_16x16x32_bf16 v[118:121], v[222:225], v[190:193], v[118:121]
	v_mfma_f32_16x16x32_bf16 v[118:121], v[226:229], v[194:197], v[118:121]
	v_mfma_f32_16x16x32_bf16 v[114:117], v[230:233], v[190:193], v[114:117]
	v_mfma_f32_16x16x32_bf16 v[114:117], v[234:237], v[194:197], v[114:117]
	v_mfma_f32_16x16x32_bf16 v[102:105], v[222:225], v[198:201], v[102:105]
	v_mfma_f32_16x16x32_bf16 v[102:105], v[226:229], v[202:205], v[102:105]
	v_mfma_f32_16x16x32_bf16 v[98:101], v[230:233], v[198:201], v[98:101]
	v_mfma_f32_16x16x32_bf16 v[98:101], v[234:237], v[202:205], v[98:101]
	v_mfma_f32_16x16x32_bf16 v[86:89], v[222:225], v[206:209], v[86:89]
	v_mfma_f32_16x16x32_bf16 v[86:89], v[226:229], v[210:213], v[86:89]
	v_mfma_f32_16x16x32_bf16 v[82:85], v[230:233], v[206:209], v[82:85]
	v_mfma_f32_16x16x32_bf16 v[82:85], v[234:237], v[210:213], v[82:85]
	v_mfma_f32_16x16x32_bf16 v[70:73], v[222:225], v[214:217], v[70:73]
	v_mfma_f32_16x16x32_bf16 v[70:73], v[226:229], v[218:221], v[70:73]
	v_mfma_f32_16x16x32_bf16 v[66:69], v[230:233], v[214:217], v[66:69]
	s_barrier
	v_mfma_f32_16x16x32_bf16 v[66:69], v[234:237], v[218:221], v[66:69]
	s_setprio 0
	s_mov_b32 m0, s95
	v_lshl_add_u64 v[238:239], v[242:243], 0, s[12:13]
	ds_read_b128 v[190:193], v169 offset:49152
	ds_read_b128 v[194:197], v169 offset:50176
	ds_read_b128 v[198:201], v169 offset:51200
	ds_read_b128 v[202:205], v169 offset:52224
	ds_read_b128 v[206:209], v169 offset:53248
	ds_read_b128 v[210:213], v169 offset:54272
	ds_read_b128 v[214:217], v169 offset:55296
	ds_read_b128 v[218:221], v169 offset:56320
	global_load_lds_dwordx4 v[238:239], off
	v_lshl_add_u64 v[250:251], v[244:245], 0, s[12:13]
	s_mov_b32 m0, s96
	s_nop 0
	global_load_lds_dwordx4 v[250:251], off
	s_waitcnt vmcnt(8)
	s_barrier
	s_waitcnt lgkmcnt(0)
	s_setprio 1
	s_waitcnt lgkmcnt(0)
	v_mfma_f32_16x16x32_bf16 v[62:65], v[142:145], v[190:193], v[62:65]
	v_mfma_f32_16x16x32_bf16 v[62:65], v[162:165], v[194:197], v[62:65]
	v_mfma_f32_16x16x32_bf16 v[58:61], v[182:185], v[190:193], v[58:61]
	v_mfma_f32_16x16x32_bf16 v[58:61], v[186:189], v[194:197], v[58:61]
	v_mfma_f32_16x16x32_bf16 v[46:49], v[142:145], v[198:201], v[46:49]
	v_mfma_f32_16x16x32_bf16 v[46:49], v[162:165], v[202:205], v[46:49]
	v_mfma_f32_16x16x32_bf16 v[42:45], v[182:185], v[198:201], v[42:45]
	v_mfma_f32_16x16x32_bf16 v[42:45], v[186:189], v[202:205], v[42:45]
	v_mfma_f32_16x16x32_bf16 v[30:33], v[142:145], v[206:209], v[30:33]
	v_mfma_f32_16x16x32_bf16 v[30:33], v[162:165], v[210:213], v[30:33]
	v_mfma_f32_16x16x32_bf16 v[26:29], v[182:185], v[206:209], v[26:29]
	v_mfma_f32_16x16x32_bf16 v[26:29], v[186:189], v[210:213], v[26:29]
	v_mfma_f32_16x16x32_bf16 v[14:17], v[142:145], v[214:217], v[14:17]
	v_mfma_f32_16x16x32_bf16 v[14:17], v[162:165], v[218:221], v[14:17]
	v_mfma_f32_16x16x32_bf16 v[10:13], v[182:185], v[214:217], v[10:13]
	s_barrier
	v_mfma_f32_16x16x32_bf16 v[10:13], v[186:189], v[218:221], v[10:13]
	s_setprio 0
	s_add_u32 s24, s48, 0x40080
	s_addc_u32 s25, s49, 0
	s_add_i32 s48, s60, s86
	v_lshl_add_u64 v[142:143], s[24:25], 0, v[134:135]
	s_mov_b32 m0, s48
	s_nop 0
	global_load_lds_dwordx4 v[142:143], off
	v_lshl_add_u64 v[250:251], s[24:25], 0, v[130:131]
	s_add_i32 m0, s48, 0x2000
	s_nop 0
	global_load_lds_dwordx4 v[250:251], off
	s_waitcnt vmcnt(6)
	s_barrier
	s_setprio 1
	v_add_u32_e32 v249, 0x10000, v167
	v_mfma_f32_16x16x32_bf16 v[54:57], v[222:225], v[190:193], v[54:57]
	v_mfma_f32_16x16x32_bf16 v[54:57], v[226:229], v[194:197], v[54:57]
	ds_read_b128 v[142:145], v249
	v_mfma_f32_16x16x32_bf16 v[50:53], v[230:233], v[190:193], v[50:53]
	v_mfma_f32_16x16x32_bf16 v[50:53], v[234:237], v[194:197], v[50:53]
	v_mfma_f32_16x16x32_bf16 v[38:41], v[222:225], v[198:201], v[38:41]
	v_mfma_f32_16x16x32_bf16 v[38:41], v[226:229], v[202:205], v[38:41]
	ds_read_b128 v[162:165], v249 offset:1024
	v_mfma_f32_16x16x32_bf16 v[34:37], v[230:233], v[198:201], v[34:37]
	v_mfma_f32_16x16x32_bf16 v[34:37], v[234:237], v[202:205], v[34:37]
	v_mfma_f32_16x16x32_bf16 v[22:25], v[222:225], v[206:209], v[22:25]
	v_mfma_f32_16x16x32_bf16 v[22:25], v[226:229], v[210:213], v[22:25]
	ds_read_b128 v[182:185], v249 offset:2048
	v_mfma_f32_16x16x32_bf16 v[18:21], v[230:233], v[206:209], v[18:21]
	v_mfma_f32_16x16x32_bf16 v[18:21], v[234:237], v[210:213], v[18:21]
	v_mfma_f32_16x16x32_bf16 v[6:9], v[222:225], v[214:217], v[6:9]
	v_mfma_f32_16x16x32_bf16 v[6:9], v[226:229], v[218:221], v[6:9]
	ds_read_b128 v[186:189], v249 offset:3072
	v_mfma_f32_16x16x32_bf16 v[2:5], v[230:233], v[214:217], v[2:5]
	s_barrier
	v_mfma_f32_16x16x32_bf16 v[2:5], v[234:237], v[218:221], v[2:5]
	s_setprio 0
	s_add_i32 s50, s50, 2
	s_add_u32 vcc_lo, vcc_lo, 0x100
	s_addc_u32 s35, s35, 0
	s_add_u32 s38, s38, 0x100
	s_addc_u32 s39, s39, 0
	s_cmp_gt_u32 s50, 13
	s_cbranch_scc0 .LBB0_165
	s_waitcnt lgkmcnt(0)
	s_and_b64 vcc, exec, s[40:41]
	s_cbranch_vccz .LBB0_168
	s_barrier

; #define PG8_STAGE(bufoff, gbase, voff) do { _Pragma("unroll") for (int _i = 0; _i < 2; ++_i) \
;         __builtin_amdgcn_global_load_lds((const unsigned*)((const char*)(gbase) + (voff)[_i]), (LAS unsigned*)(lds + (bufoff) + ldsw + _i * 8192), 16, 0, 0); } while (0)
; #define PG8_LDA(dst, b, h) do { _Pragma("unroll") for (int m = 0; m < 4; ++m) _Pragma("unroll") for (int k = 0; k < 2; ++k) dst[m][k] = *(const LAS bf16x8*)(lds + PG8_SA(b, h) + aoff + m * 2048 + k * 1024); } while (0)
; #define PG8_LDB(dst, b, h) do { _Pragma("unroll") for (int n = 0; n < 2; ++n) _Pragma("unroll") for (int k = 0; k < 2; ++k) dst[n][k] = *(const LAS bf16x8*)(lds + PG8_SB(b, h) + boff + n * 2048 + k * 1024); } while (0)
; #define PG8_MMA(ai, bj, At, Bt) do { __builtin_amdgcn_s_setprio(1); _Pragma("unroll") for (int m = 0; m < 4; ++m) _Pragma("unroll") for (int n = 0; n < 2; ++n) _Pragma("unroll") for (int k = 0; k < 2; ++k) \
;         acc[ai][bj][m][n] = __builtin_amdgcn_mfma_f32_16x16x32_bf16(Bt[n][k], At[m][k], acc[ai][bj][m][n], 0, 0, 0); __builtin_amdgcn_s_setprio(0); } while (0)
; #define PG8_WAIT_L(n) asm volatile("s_waitcnt lgkmcnt(" #n ")" ::: "memory")
; #define PG8_BAR __builtin_amdgcn_s_barrier()
; #define PG8_SCHED __builtin_amdgcn_sched_barrier(0)
; template <class Epi, class Sched>
; __device__ __forceinline__ void gemm_phase(LAS unsigned char* lds, const Gemm g, const Sched& S, const Epi& E) {
;     ...
;         for (int t = 0; t < nt; t += 2) {
;             const bool last = (t == nt - 2);
;             const char* a1 = cA + (size_t)(t + 1) * kstep;
;             const char* a2 = last ? nA : cA + (size_t)(t + 2) * kstep; const char* b2 = last ? nB : cB + (size_t)(t + 2) * kstep;
;             const char* a3 = a2 + kstep; const char* b3 = b2 + kstep;
;             PG8_LDB(B0, 0, 0); PG8_SCHED; PG8_LDA(At, 0, 0); PG8_STAGE(PG8_SA(1, 1), a1 + hstep, voffA);
;             PG8_WAIT_L(8); PG8_BAR; PG8_WAIT_L(0); PG8_MMA(0, 0, At, B0); PG8_BAR; PG8_SCHED;
;             PG8_LDB(B1, 0, 1); PG8_STAGE(PG8_SB(0, 0), b2, voffB);
;             PG8_BAR; PG8_WAIT_L(0); PG8_MMA(0, 1, At, B1); PG8_BAR;
;             PG8_LDA(At, 0, 1); PG8_STAGE(PG8_SA(0, 0), a2, voffA);
;             PG8_BAR; PG8_WAIT_L(0); PG8_MMA(1, 0, At, B0); PG8_BAR; PG8_SCHED;
.LBB0_416:
	s_add_u32 s24, s0, 0xfffc0080
	s_addc_u32 s25, s1, -1
	s_add_i32 s39, 0, 0x10000
	v_add_u32_e32 v142, s39, v144
	s_cmp_eq_u32 s38, 12
	s_cselect_b32 vcc_hi, s77, s25
	s_cselect_b32 vcc_lo, s76, s24
	s_cselect_b32 s37, s47, s50
	s_cselect_b32 s36, s61, s35
	v_lshl_add_u64 v[142:143], s[0:1], 0, v[140:141]
	s_add_i32 m0, s93, 0xc000
	ds_read_b128 v[194:197], v162
	ds_read_b128 v[198:201], v162 offset:1024
	ds_read_b128 v[202:205], v162 offset:2048
	ds_read_b128 v[206:209], v162 offset:3072
	ds_read_b128 v[210:213], v162 offset:4096
	ds_read_b128 v[214:217], v162 offset:5120
	ds_read_b128 v[218:221], v162 offset:6144
	ds_read_b128 v[222:225], v162 offset:7168
	global_load_lds_dwordx4 v[142:143], off
	v_lshl_add_u64 v[250:251], s[0:1], 0, v[138:139]
	s_add_i32 m0, s93, 0xe000
	s_nop 0
	global_load_lds_dwordx4 v[250:251], off
	s_waitcnt lgkmcnt(8)
	s_barrier
	s_waitcnt lgkmcnt(0)
	s_setprio 1
	s_waitcnt lgkmcnt(0)
	v_mfma_f32_16x16x32_bf16 v[126:129], v[164:167], v[194:197], v[126:129]
	v_mfma_f32_16x16x32_bf16 v[126:129], v[182:185], v[198:201], v[126:129]
	v_mfma_f32_16x16x32_bf16 v[122:125], v[186:189], v[194:197], v[122:125]
	v_mfma_f32_16x16x32_bf16 v[122:125], v[190:193], v[198:201], v[122:125]
	v_mfma_f32_16x16x32_bf16 v[118:121], v[164:167], v[202:205], v[118:121]
	v_mfma_f32_16x16x32_bf16 v[118:121], v[182:185], v[206:209], v[118:121]
	v_mfma_f32_16x16x32_bf16 v[110:113], v[186:189], v[202:205], v[110:113]
	v_mfma_f32_16x16x32_bf16 v[110:113], v[190:193], v[206:209], v[110:113]
	v_mfma_f32_16x16x32_bf16 v[102:105], v[164:167], v[210:213], v[102:105]
	v_mfma_f32_16x16x32_bf16 v[102:105], v[182:185], v[214:217], v[102:105]
	v_mfma_f32_16x16x32_bf16 v[94:97], v[186:189], v[210:213], v[94:97]
	v_mfma_f32_16x16x32_bf16 v[94:97], v[190:193], v[214:217], v[94:97]
	v_mfma_f32_16x16x32_bf16 v[86:89], v[164:167], v[218:221], v[86:89]
	v_mfma_f32_16x16x32_bf16 v[86:89], v[182:185], v[222:225], v[86:89]
	v_mfma_f32_16x16x32_bf16 v[78:81], v[186:189], v[218:221], v[78:81]
	s_barrier
	v_mfma_f32_16x16x32_bf16 v[78:81], v[190:193], v[222:225], v[78:81]
	s_setprio 0
	s_add_i32 s51, 0, 0x14000
	v_add_u32_e32 v142, s51, v144
	s_add_i32 s24, s39, s86
	ds_read_b128 v[226:229], v142
	ds_read_b128 v[230:233], v142 offset:1024
	ds_read_b128 v[234:237], v142 offset:2048
	ds_read_b128 v[238:241], v142 offset:3072
	v_lshl_add_u64 v[142:143], s[36:37], 0, v[134:135]
	s_mov_b32 m0, s24
	v_lshl_add_u64 v[168:169], s[36:37], 0, v[130:131]
	global_load_lds_dwordx4 v[142:143], off
	s_add_i32 m0, s24, 0x2000
	s_nop 0
	global_load_lds_dwordx4 v[168:169], off
	s_barrier
	s_waitcnt lgkmcnt(0)
	s_setprio 1
	s_waitcnt lgkmcnt(0)
	v_mfma_f32_16x16x32_bf16 v[114:117], v[226:229], v[194:197], v[114:117]
	v_mfma_f32_16x16x32_bf16 v[114:117], v[230:233], v[198:201], v[114:117]
	v_mfma_f32_16x16x32_bf16 v[106:109], v[234:237], v[194:197], v[106:109]
	v_mfma_f32_16x16x32_bf16 v[106:109], v[238:241], v[198:201], v[106:109]
	v_mfma_f32_16x16x32_bf16 v[98:101], v[226:229], v[202:205], v[98:101]
	v_mfma_f32_16x16x32_bf16 v[98:101], v[230:233], v[206:209], v[98:101]
	v_mfma_f32_16x16x32_bf16 v[90:93], v[234:237], v[202:205], v[90:93]
	v_mfma_f32_16x16x32_bf16 v[90:93], v[238:241], v[206:209], v[90:93]
	v_mfma_f32_16x16x32_bf16 v[82:85], v[226:229], v[210:213], v[82:85]
	v_mfma_f32_16x16x32_bf16 v[82:85], v[230:233], v[214:217], v[82:85]
	v_mfma_f32_16x16x32_bf16 v[74:77], v[234:237], v[210:213], v[74:77]
	v_mfma_f32_16x16x32_bf16 v[74:77], v[238:241], v[214:217], v[74:77]
	v_mfma_f32_16x16x32_bf16 v[70:73], v[226:229], v[218:221], v[70:73]
	v_mfma_f32_16x16x32_bf16 v[70:73], v[230:233], v[222:225], v[70:73]
	v_mfma_f32_16x16x32_bf16 v[66:69], v[234:237], v[218:221], v[66:69]
	s_barrier
	v_mfma_f32_16x16x32_bf16 v[66:69], v[238:241], v[222:225], v[66:69]
	s_setprio 0
	s_mov_b32 m0, s93
	v_lshl_add_u64 v[242:243], vcc, 0, v[136:137]
	ds_read_b128 v[194:197], v162 offset:16384
	ds_read_b128 v[198:201], v162 offset:17408
	ds_read_b128 v[202:205], v162 offset:18432
	ds_read_b128 v[206:209], v162 offset:19456
	ds_read_b128 v[210:213], v162 offset:20480
	ds_read_b128 v[214:217], v162 offset:21504
	ds_read_b128 v[218:221], v162 offset:22528
	ds_read_b128 v[222:225], v162 offset:23552
	global_load_lds_dwordx4 v[242:243], off
	v_lshl_add_u64 v[244:245], vcc, 0, v[132:133]
	s_mov_b32 m0, s94
	s_nop 0
	global_load_lds_dwordx4 v[244:245], off
	s_waitcnt vmcnt(8)
	s_barrier
	s_waitcnt lgkmcnt(0)
	s_setprio 1
	s_waitcnt lgkmcnt(0)
	v_mfma_f32_16x16x32_bf16 v[62:65], v[164:167], v[194:197], v[62:65]
	v_mfma_f32_16x16x32_bf16 v[62:65], v[182:185], v[198:201], v[62:65]
	v_mfma_f32_16x16x32_bf16 v[58:61], v[186:189], v[194:197], v[58:61]
	v_mfma_f32_16x16x32_bf16 v[58:61], v[190:193], v[198:201], v[58:61]
	v_mfma_f32_16x16x32_bf16 v[54:57], v[164:167], v[202:205], v[54:57]
	v_mfma_f32_16x16x32_bf16 v[54:57], v[182:185], v[206:209], v[54:57]
	v_mfma_f32_16x16x32_bf16 v[46:49], v[186:189], v[202:205], v[46:49]
	v_mfma_f32_16x16x32_bf16 v[46:49], v[190:193], v[206:209], v[46:49]
	v_mfma_f32_16x16x32_bf16 v[38:41], v[164:167], v[210:213], v[38:41]
	v_mfma_f32_16x16x32_bf16 v[38:41], v[182:185], v[214:217], v[38:41]
	v_mfma_f32_16x16x32_bf16 v[30:33], v[186:189], v[210:213], v[30:33]
	v_mfma_f32_16x16x32_bf16 v[30:33], v[190:193], v[214:217], v[30:33]
	v_mfma_f32_16x16x32_bf16 v[22:25], v[164:167], v[218:221], v[22:25]
	v_mfma_f32_16x16x32_bf16 v[22:25], v[182:185], v[222:225], v[22:25]
	v_mfma_f32_16x16x32_bf16 v[14:17], v[186:189], v[218:221], v[14:17]
	s_barrier
; #define PG8_STAGE(bufoff, gbase, voff) do { _Pragma("unroll") for (int _i = 0; _i < 2; ++_i) \
;         __builtin_amdgcn_global_load_lds((const unsigned*)((const char*)(gbase) + (voff)[_i]), (LAS unsigned*)(lds + (bufoff) + ldsw + _i * 8192), 16, 0, 0); } while (0)
; #define PG8_LDA(dst, b, h) do { _Pragma("unroll") for (int m = 0; m < 4; ++m) _Pragma("unroll") for (int k = 0; k < 2; ++k) dst[m][k] = *(const LAS bf16x8*)(lds + PG8_SA(b, h) + aoff + m * 2048 + k * 1024); } while (0)
; #define PG8_LDB(dst, b, h) do { _Pragma("unroll") for (int n = 0; n < 2; ++n) _Pragma("unroll") for (int k = 0; k < 2; ++k) dst[n][k] = *(const LAS bf16x8*)(lds + PG8_SB(b, h) + boff + n * 2048 + k * 1024); } while (0)
; #define PG8_MMA(ai, bj, At, Bt) do { __builtin_amdgcn_s_setprio(1); _Pragma("unroll") for (int m = 0; m < 4; ++m) _Pragma("unroll") for (int n = 0; n < 2; ++n) _Pragma("unroll") for (int k = 0; k < 2; ++k) \
;         acc[ai][bj][m][n] = __builtin_amdgcn_mfma_f32_16x16x32_bf16(Bt[n][k], At[m][k], acc[ai][bj][m][n], 0, 0, 0); __builtin_amdgcn_s_setprio(0); } while (0)
; #define PG8_WAIT_V(n) asm volatile("s_waitcnt vmcnt(" #n ")" ::: "memory")
; #define PG8_WAIT_L(n) asm volatile("s_waitcnt lgkmcnt(" #n ")" ::: "memory")
; #define PG8_BAR __builtin_amdgcn_s_barrier()
; #define PG8_SCHED __builtin_amdgcn_sched_barrier(0)
; template <class Epi, class Sched>
; __device__ __forceinline__ void gemm_phase(LAS unsigned char* lds, const Gemm g, const Sched& S, const Epi& E) {
;     ...
;             PG8_STAGE(PG8_SB(0, 1), b2 + hstep, voffB);
;             PG8_WAIT_V(6); PG8_BAR; PG8_MMA(1, 1, At, B1); PG8_BAR;
;             PG8_LDB(B0, 1, 0); PG8_SCHED; PG8_LDA(At, 1, 0); PG8_STAGE(PG8_SA(0, 1), a2 + hstep, voffA);
;             PG8_WAIT_L(8); PG8_BAR; PG8_WAIT_L(0); PG8_MMA(0, 0, At, B0); PG8_BAR; PG8_SCHED;
;             PG8_LDB(B1, 1, 1); PG8_STAGE(PG8_SB(1, 0), b3, voffB);
	v_mfma_f32_16x16x32_bf16 v[14:17], v[190:193], v[222:225], v[14:17]
	s_setprio 0
	s_add_u32 s24, s36, 0x40000
	s_addc_u32 s25, s37, 0
	s_add_i32 s39, s51, s86
	v_lshl_add_u64 v[164:165], s[24:25], 0, v[134:135]
	s_mov_b32 m0, s39
	s_nop 0
	global_load_lds_dwordx4 v[164:165], off
	v_lshl_add_u64 v[250:251], s[24:25], 0, v[130:131]
	s_add_i32 m0, s39, 0x2000
	s_nop 0
	global_load_lds_dwordx4 v[250:251], off
	s_waitcnt vmcnt(6)
	s_barrier
	s_setprio 1
	v_add_u32_e32 v249, 0x18000, v144
	v_mfma_f32_16x16x32_bf16 v[50:53], v[226:229], v[194:197], v[50:53]
	v_mfma_f32_16x16x32_bf16 v[50:53], v[230:233], v[198:201], v[50:53]
	ds_read_b128 v[164:167], v249
	v_mfma_f32_16x16x32_bf16 v[42:45], v[234:237], v[194:197], v[42:45]
	v_mfma_f32_16x16x32_bf16 v[42:45], v[238:241], v[198:201], v[42:45]
	v_mfma_f32_16x16x32_bf16 v[34:37], v[226:229], v[202:205], v[34:37]
	v_mfma_f32_16x16x32_bf16 v[34:37], v[230:233], v[206:209], v[34:37]
	ds_read_b128 v[182:185], v249 offset:1024
	v_mfma_f32_16x16x32_bf16 v[26:29], v[234:237], v[202:205], v[26:29]
	v_mfma_f32_16x16x32_bf16 v[26:29], v[238:241], v[206:209], v[26:29]
	v_mfma_f32_16x16x32_bf16 v[18:21], v[226:229], v[210:213], v[18:21]
	v_mfma_f32_16x16x32_bf16 v[18:21], v[230:233], v[214:217], v[18:21]
	ds_read_b128 v[186:189], v249 offset:2048
	v_mfma_f32_16x16x32_bf16 v[10:13], v[234:237], v[210:213], v[10:13]
	v_mfma_f32_16x16x32_bf16 v[10:13], v[238:241], v[214:217], v[10:13]
	v_mfma_f32_16x16x32_bf16 v[6:9], v[226:229], v[218:221], v[6:9]
	v_mfma_f32_16x16x32_bf16 v[6:9], v[230:233], v[222:225], v[6:9]
	ds_read_b128 v[190:193], v249 offset:3072
	v_mfma_f32_16x16x32_bf16 v[2:5], v[234:237], v[218:221], v[2:5]
	s_barrier
	v_mfma_f32_16x16x32_bf16 v[2:5], v[238:241], v[222:225], v[2:5]
	s_setprio 0
	s_add_i32 s39, 0, 0x18000
	v_add_u32_e32 v163, s39, v144
	s_add_u32 s24, vcc_lo, 0x40000
	s_addc_u32 s25, vcc_hi, 0
	s_mov_b32 m0, s95
	v_lshl_add_u64 v[226:227], s[24:25], 0, v[136:137]
	ds_read_b128 v[194:197], v162 offset:32768
	ds_read_b128 v[198:201], v162 offset:33792
	ds_read_b128 v[202:205], v162 offset:34816
	ds_read_b128 v[206:209], v162 offset:35840
	ds_read_b128 v[210:213], v162 offset:36864
	ds_read_b128 v[214:217], v162 offset:37888
	ds_read_b128 v[218:221], v162 offset:38912
	ds_read_b128 v[222:225], v162 offset:39936
	global_load_lds_dwordx4 v[226:227], off
	v_lshl_add_u64 v[250:251], s[24:25], 0, v[132:133]
	s_mov_b32 m0, s96
	s_nop 0
	global_load_lds_dwordx4 v[250:251], off
	s_waitcnt lgkmcnt(8)
	s_barrier
	s_waitcnt lgkmcnt(0)
	s_setprio 1
	s_waitcnt lgkmcnt(0)
	v_mfma_f32_16x16x32_bf16 v[126:129], v[164:167], v[194:197], v[126:129]
	v_mfma_f32_16x16x32_bf16 v[126:129], v[182:185], v[198:201], v[126:129]
	v_mfma_f32_16x16x32_bf16 v[122:125], v[186:189], v[194:197], v[122:125]
	v_mfma_f32_16x16x32_bf16 v[122:125], v[190:193], v[198:201], v[122:125]
	v_mfma_f32_16x16x32_bf16 v[118:121], v[164:167], v[202:205], v[118:121]
	v_mfma_f32_16x16x32_bf16 v[118:121], v[182:185], v[206:209], v[118:121]
	v_mfma_f32_16x16x32_bf16 v[110:113], v[186:189], v[202:205], v[110:113]
	v_mfma_f32_16x16x32_bf16 v[110:113], v[190:193], v[206:209], v[110:113]
	v_mfma_f32_16x16x32_bf16 v[102:105], v[164:167], v[210:213], v[102:105]
	v_mfma_f32_16x16x32_bf16 v[102:105], v[182:185], v[214:217], v[102:105]
	v_mfma_f32_16x16x32_bf16 v[94:97], v[186:189], v[210:213], v[94:97]
	v_mfma_f32_16x16x32_bf16 v[94:97], v[190:193], v[214:217], v[94:97]
	v_mfma_f32_16x16x32_bf16 v[86:89], v[164:167], v[218:221], v[86:89]
	v_mfma_f32_16x16x32_bf16 v[86:89], v[182:185], v[222:225], v[86:89]
	v_mfma_f32_16x16x32_bf16 v[78:81], v[186:189], v[218:221], v[78:81]
	s_barrier
	v_mfma_f32_16x16x32_bf16 v[78:81], v[190:193], v[222:225], v[78:81]
	s_setprio 0
	s_add_i32 s51, 0, 0x1c000
	s_add_i32 s24, s39, s86
	v_add_u32_e32 v163, s51, v144
	v_lshl_add_u64 v[142:143], v[142:143], 0, s[12:13]
	s_mov_b32 m0, s24
	ds_read_b128 v[226:229], v163
	ds_read_b128 v[230:233], v163 offset:1024
	ds_read_b128 v[234:237], v163 offset:2048
	ds_read_b128 v[238:241], v163 offset:3072
	global_load_lds_dwordx4 v[142:143], off
	v_lshl_add_u64 v[250:251], v[168:169], 0, s[12:13]
	s_add_i32 m0, s24, 0x2000
	s_nop 0
	global_load_lds_dwordx4 v[250:251], off
	s_barrier
; #define PG8_STAGE(bufoff, gbase, voff) do { _Pragma("unroll") for (int _i = 0; _i < 2; ++_i) \
;         __builtin_amdgcn_global_load_lds((const unsigned*)((const char*)(gbase) + (voff)[_i]), (LAS unsigned*)(lds + (bufoff) + ldsw + _i * 8192), 16, 0, 0); } while (0)
; #define PG8_LDA(dst, b, h) do { _Pragma("unroll") for (int m = 0; m < 4; ++m) _Pragma("unroll") for (int k = 0; k < 2; ++k) dst[m][k] = *(const LAS bf16x8*)(lds + PG8_SA(b, h) + aoff + m * 2048 + k * 1024); } while (0)
; #define PG8_MMA(ai, bj, At, Bt) do { __builtin_amdgcn_s_setprio(1); _Pragma("unroll") for (int m = 0; m < 4; ++m) _Pragma("unroll") for (int n = 0; n < 2; ++n) _Pragma("unroll") for (int k = 0; k < 2; ++k) \
;         acc[ai][bj][m][n] = __builtin_amdgcn_mfma_f32_16x16x32_bf16(Bt[n][k], At[m][k], acc[ai][bj][m][n], 0, 0, 0); __builtin_amdgcn_s_setprio(0); } while (0)
; #define PG8_WAIT_V(n) asm volatile("s_waitcnt vmcnt(" #n ")" ::: "memory")
; #define PG8_WAIT_L(n) asm volatile("s_waitcnt lgkmcnt(" #n ")" ::: "memory")
; #define PG8_BAR __builtin_amdgcn_s_barrier()
; #define PG8_SCHED __builtin_amdgcn_sched_barrier(0)
; template <class Epi, class Sched>
; __device__ __forceinline__ void gemm_phase(LAS unsigned char* lds, const Gemm g, const Sched& S, const Epi& E) {
;     ...
;             PG8_BAR; PG8_WAIT_L(0); PG8_MMA(0, 1, At, B1); PG8_BAR;
;             PG8_LDA(At, 1, 1); PG8_STAGE(PG8_SA(1, 0), a3, voffA);
;             PG8_BAR; PG8_WAIT_L(0); PG8_MMA(1, 0, At, B0); PG8_BAR; PG8_SCHED;
;             PG8_STAGE(PG8_SB(1, 1), b3 + hstep, voffB);
;             PG8_WAIT_V(6); PG8_BAR; PG8_MMA(1, 1, At, B1); PG8_BAR;
;         }
;         if (wr == 0) PG8_BAR;
	s_waitcnt lgkmcnt(0)
	s_setprio 1
	s_waitcnt lgkmcnt(0)
	v_mfma_f32_16x16x32_bf16 v[114:117], v[226:229], v[194:197], v[114:117]
	v_mfma_f32_16x16x32_bf16 v[114:117], v[230:233], v[198:201], v[114:117]
	v_mfma_f32_16x16x32_bf16 v[106:109], v[234:237], v[194:197], v[106:109]
	v_mfma_f32_16x16x32_bf16 v[106:109], v[238:241], v[198:201], v[106:109]
	v_mfma_f32_16x16x32_bf16 v[98:101], v[226:229], v[202:205], v[98:101]
	v_mfma_f32_16x16x32_bf16 v[98:101], v[230:233], v[206:209], v[98:101]
	v_mfma_f32_16x16x32_bf16 v[90:93], v[234:237], v[202:205], v[90:93]
	v_mfma_f32_16x16x32_bf16 v[90:93], v[238:241], v[206:209], v[90:93]
	v_mfma_f32_16x16x32_bf16 v[82:85], v[226:229], v[210:213], v[82:85]
	v_mfma_f32_16x16x32_bf16 v[82:85], v[230:233], v[214:217], v[82:85]
	v_mfma_f32_16x16x32_bf16 v[74:77], v[234:237], v[210:213], v[74:77]
	v_mfma_f32_16x16x32_bf16 v[74:77], v[238:241], v[214:217], v[74:77]
	v_mfma_f32_16x16x32_bf16 v[70:73], v[226:229], v[218:221], v[70:73]
	v_mfma_f32_16x16x32_bf16 v[70:73], v[230:233], v[222:225], v[70:73]
	v_mfma_f32_16x16x32_bf16 v[66:69], v[234:237], v[218:221], v[66:69]
	s_barrier
	v_mfma_f32_16x16x32_bf16 v[66:69], v[238:241], v[222:225], v[66:69]
	s_setprio 0
	s_mov_b32 m0, s97
	v_lshl_add_u64 v[142:143], v[242:243], 0, s[12:13]
	ds_read_b128 v[194:197], v162 offset:49152
	ds_read_b128 v[198:201], v162 offset:50176
	ds_read_b128 v[202:205], v162 offset:51200
	ds_read_b128 v[206:209], v162 offset:52224
	ds_read_b128 v[210:213], v162 offset:53248
	ds_read_b128 v[214:217], v162 offset:54272
	ds_read_b128 v[218:221], v162 offset:55296
	ds_read_b128 v[222:225], v162 offset:56320
	global_load_lds_dwordx4 v[142:143], off
	v_lshl_add_u64 v[250:251], v[244:245], 0, s[12:13]
	s_mov_b32 m0, s98
	s_nop 0
	global_load_lds_dwordx4 v[250:251], off
	s_waitcnt vmcnt(8)
	s_barrier
	s_waitcnt lgkmcnt(0)
	s_setprio 1
	s_waitcnt lgkmcnt(0)
	v_mfma_f32_16x16x32_bf16 v[62:65], v[164:167], v[194:197], v[62:65]
	v_mfma_f32_16x16x32_bf16 v[62:65], v[182:185], v[198:201], v[62:65]
	v_mfma_f32_16x16x32_bf16 v[58:61], v[186:189], v[194:197], v[58:61]
	v_mfma_f32_16x16x32_bf16 v[58:61], v[190:193], v[198:201], v[58:61]
	v_mfma_f32_16x16x32_bf16 v[54:57], v[164:167], v[202:205], v[54:57]
	v_mfma_f32_16x16x32_bf16 v[54:57], v[182:185], v[206:209], v[54:57]
	v_mfma_f32_16x16x32_bf16 v[46:49], v[186:189], v[202:205], v[46:49]
	v_mfma_f32_16x16x32_bf16 v[46:49], v[190:193], v[206:209], v[46:49]
	v_mfma_f32_16x16x32_bf16 v[38:41], v[164:167], v[210:213], v[38:41]
	v_mfma_f32_16x16x32_bf16 v[38:41], v[182:185], v[214:217], v[38:41]
	v_mfma_f32_16x16x32_bf16 v[30:33], v[186:189], v[210:213], v[30:33]
	v_mfma_f32_16x16x32_bf16 v[30:33], v[190:193], v[214:217], v[30:33]
	v_mfma_f32_16x16x32_bf16 v[22:25], v[164:167], v[218:221], v[22:25]
	v_mfma_f32_16x16x32_bf16 v[22:25], v[182:185], v[222:225], v[22:25]
	v_mfma_f32_16x16x32_bf16 v[14:17], v[186:189], v[218:221], v[14:17]
	s_barrier
	v_mfma_f32_16x16x32_bf16 v[14:17], v[190:193], v[222:225], v[14:17]
	s_setprio 0
	s_add_u32 s24, s36, 0x40080
	s_addc_u32 s25, s37, 0
	s_add_i32 s36, s51, s86
	v_lshl_add_u64 v[142:143], s[24:25], 0, v[134:135]
	s_mov_b32 m0, s36
	s_nop 0
	global_load_lds_dwordx4 v[142:143], off
	v_lshl_add_u64 v[250:251], s[24:25], 0, v[130:131]
	s_add_i32 m0, s36, 0x2000
	s_nop 0
	global_load_lds_dwordx4 v[250:251], off
	s_waitcnt vmcnt(6)
	s_barrier
	s_setprio 1
	v_add_u32_e32 v249, 0x10000, v144
	v_mfma_f32_16x16x32_bf16 v[50:53], v[226:229], v[194:197], v[50:53]
	v_mfma_f32_16x16x32_bf16 v[50:53], v[230:233], v[198:201], v[50:53]
	ds_read_b128 v[164:167], v249
	v_mfma_f32_16x16x32_bf16 v[42:45], v[234:237], v[194:197], v[42:45]
	v_mfma_f32_16x16x32_bf16 v[42:45], v[238:241], v[198:201], v[42:45]
	v_mfma_f32_16x16x32_bf16 v[34:37], v[226:229], v[202:205], v[34:37]
	v_mfma_f32_16x16x32_bf16 v[34:37], v[230:233], v[206:209], v[34:37]
	ds_read_b128 v[182:185], v249 offset:1024
	v_mfma_f32_16x16x32_bf16 v[26:29], v[234:237], v[202:205], v[26:29]
	v_mfma_f32_16x16x32_bf16 v[26:29], v[238:241], v[206:209], v[26:29]
	v_mfma_f32_16x16x32_bf16 v[18:21], v[226:229], v[210:213], v[18:21]
	v_mfma_f32_16x16x32_bf16 v[18:21], v[230:233], v[214:217], v[18:21]
	ds_read_b128 v[186:189], v249 offset:2048
	v_mfma_f32_16x16x32_bf16 v[10:13], v[234:237], v[210:213], v[10:13]
	v_mfma_f32_16x16x32_bf16 v[10:13], v[238:241], v[214:217], v[10:13]
	v_mfma_f32_16x16x32_bf16 v[6:9], v[226:229], v[218:221], v[6:9]
	v_mfma_f32_16x16x32_bf16 v[6:9], v[230:233], v[222:225], v[6:9]
	ds_read_b128 v[190:193], v249 offset:3072
	v_mfma_f32_16x16x32_bf16 v[2:5], v[234:237], v[218:221], v[2:5]
	s_barrier
	v_mfma_f32_16x16x32_bf16 v[2:5], v[238:241], v[222:225], v[2:5]
	s_setprio 0
	s_add_i32 s38, s38, 2
	s_add_u32 s35, s35, 0x100
	s_addc_u32 s50, s50, 0
	s_add_u32 s0, s0, 0x100
	s_addc_u32 s1, s1, 0
	s_cmp_gt_u32 s38, 13
	s_cbranch_scc0 .LBB0_416
	s_waitcnt lgkmcnt(0)
	s_and_b64 vcc, exec, s[44:45]
	s_cbranch_vccz .LBB0_419
	s_barrier

; #define PG8_STAGE(bufoff, gbase, voff) do { _Pragma("unroll") for (int _i = 0; _i < 2; ++_i) \
;         __builtin_amdgcn_global_load_lds((const unsigned*)((const char*)(gbase) + (voff)[_i]), (LAS unsigned*)(lds + (bufoff) + ldsw + _i * 8192), 16, 0, 0); } while (0)
; #define PG8_LDA(dst, b, h) do { _Pragma("unroll") for (int m = 0; m < 4; ++m) _Pragma("unroll") for (int k = 0; k < 2; ++k) dst[m][k] = *(const LAS bf16x8*)(lds + PG8_SA(b, h) + aoff + m * 2048 + k * 1024); } while (0)
; #define PG8_LDB(dst, b, h) do { _Pragma("unroll") for (int n = 0; n < 2; ++n) _Pragma("unroll") for (int k = 0; k < 2; ++k) dst[n][k] = *(const LAS bf16x8*)(lds + PG8_SB(b, h) + boff + n * 2048 + k * 1024); } while (0)
; #define PG8_MMA(ai, bj, At, Bt) do { __builtin_amdgcn_s_setprio(1); _Pragma("unroll") for (int m = 0; m < 4; ++m) _Pragma("unroll") for (int n = 0; n < 2; ++n) _Pragma("unroll") for (int k = 0; k < 2; ++k) \
;         acc[ai][bj][m][n] = __builtin_amdgcn_mfma_f32_16x16x32_bf16(Bt[n][k], At[m][k], acc[ai][bj][m][n], 0, 0, 0); __builtin_amdgcn_s_setprio(0); } while (0)
; #define PG8_WAIT_L(n) asm volatile("s_waitcnt lgkmcnt(" #n ")" ::: "memory")
; #define PG8_BAR __builtin_amdgcn_s_barrier()
; #define PG8_SCHED __builtin_amdgcn_sched_barrier(0)
; template <class Epi, class Sched>
; __device__ __forceinline__ void gemm_phase(LAS unsigned char* lds, const Gemm g, const Sched& S, const Epi& E) {
;     ...
;         for (int t = 0; t < nt; t += 2) {
;             const bool last = (t == nt - 2);
;             const char* a1 = cA + (size_t)(t + 1) * kstep;
;             const char* a2 = last ? nA : cA + (size_t)(t + 2) * kstep; const char* b2 = last ? nB : cB + (size_t)(t + 2) * kstep;
;             const char* a3 = a2 + kstep; const char* b3 = b2 + kstep;
;             PG8_LDB(B0, 0, 0); PG8_SCHED; PG8_LDA(At, 0, 0); PG8_STAGE(PG8_SA(1, 1), a1 + hstep, voffA);
;             PG8_WAIT_L(8); PG8_BAR; PG8_WAIT_L(0); PG8_MMA(0, 0, At, B0); PG8_BAR; PG8_SCHED;
;             PG8_LDB(B1, 0, 1); PG8_STAGE(PG8_SB(0, 0), b2, voffB);
;             PG8_BAR; PG8_WAIT_L(0); PG8_MMA(0, 1, At, B1); PG8_BAR;
;             PG8_LDA(At, 0, 1); PG8_STAGE(PG8_SA(0, 0), a2, voffA);
;             PG8_BAR; PG8_WAIT_L(0); PG8_MMA(1, 0, At, B0); PG8_BAR; PG8_SCHED;
.LBB0_557:
	s_add_u32 s24, s0, 0xfffc0080
	s_addc_u32 s25, s1, -1
	s_add_i32 s39, 0, 0x10000
	v_add_u32_e32 v162, s39, v164
	s_cmp_eq_u32 s38, 12
	s_cselect_b32 vcc_hi, s77, s25
	s_cselect_b32 vcc_lo, s76, s24
	s_cselect_b32 s49, s45, s50
	s_cselect_b32 s48, s47, s35
	v_lshl_add_u64 v[162:163], s[0:1], 0, v[140:141]
	s_add_i32 m0, s95, 0xc000
	ds_read_b128 v[194:197], v166
	ds_read_b128 v[198:201], v166 offset:1024
	ds_read_b128 v[202:205], v166 offset:2048
	ds_read_b128 v[206:209], v166 offset:3072
	ds_read_b128 v[210:213], v166 offset:4096
	ds_read_b128 v[214:217], v166 offset:5120
	ds_read_b128 v[218:221], v166 offset:6144
	ds_read_b128 v[222:225], v166 offset:7168
	global_load_lds_dwordx4 v[162:163], off
	v_lshl_add_u64 v[250:251], s[0:1], 0, v[138:139]
	s_add_i32 m0, s95, 0xe000
	s_nop 0
	global_load_lds_dwordx4 v[250:251], off
	s_waitcnt lgkmcnt(8)
	s_barrier
	s_waitcnt lgkmcnt(0)
	s_setprio 1
	s_waitcnt lgkmcnt(0)
	v_mfma_f32_16x16x32_bf16 v[126:129], v[142:145], v[194:197], v[126:129]
	v_mfma_f32_16x16x32_bf16 v[126:129], v[182:185], v[198:201], v[126:129]
	v_mfma_f32_16x16x32_bf16 v[122:125], v[186:189], v[194:197], v[122:125]
	v_mfma_f32_16x16x32_bf16 v[122:125], v[190:193], v[198:201], v[122:125]
	v_mfma_f32_16x16x32_bf16 v[110:113], v[142:145], v[202:205], v[110:113]
	v_mfma_f32_16x16x32_bf16 v[110:113], v[182:185], v[206:209], v[110:113]
	v_mfma_f32_16x16x32_bf16 v[106:109], v[186:189], v[202:205], v[106:109]
	v_mfma_f32_16x16x32_bf16 v[106:109], v[190:193], v[206:209], v[106:109]
	v_mfma_f32_16x16x32_bf16 v[94:97], v[142:145], v[210:213], v[94:97]
	v_mfma_f32_16x16x32_bf16 v[94:97], v[182:185], v[214:217], v[94:97]
	v_mfma_f32_16x16x32_bf16 v[90:93], v[186:189], v[210:213], v[90:93]
	v_mfma_f32_16x16x32_bf16 v[90:93], v[190:193], v[214:217], v[90:93]
	v_mfma_f32_16x16x32_bf16 v[78:81], v[142:145], v[218:221], v[78:81]
	v_mfma_f32_16x16x32_bf16 v[78:81], v[182:185], v[222:225], v[78:81]
	v_mfma_f32_16x16x32_bf16 v[74:77], v[186:189], v[218:221], v[74:77]
	s_barrier
	v_mfma_f32_16x16x32_bf16 v[74:77], v[190:193], v[222:225], v[74:77]
	s_setprio 0
	s_add_i32 s51, 0, 0x14000
	v_add_u32_e32 v162, s51, v164
	s_add_i32 s24, s39, s94
	ds_read_b128 v[226:229], v162
	ds_read_b128 v[230:233], v162 offset:1024
	ds_read_b128 v[234:237], v162 offset:2048
	ds_read_b128 v[238:241], v162 offset:3072
	v_lshl_add_u64 v[162:163], s[48:49], 0, v[134:135]
	s_mov_b32 m0, s24
	v_lshl_add_u64 v[168:169], s[48:49], 0, v[130:131]
	global_load_lds_dwordx4 v[162:163], off
	s_add_i32 m0, s24, 0x2000
	s_nop 0
	global_load_lds_dwordx4 v[168:169], off
	s_barrier
	s_waitcnt lgkmcnt(0)
	s_setprio 1
	s_waitcnt lgkmcnt(0)
	v_mfma_f32_16x16x32_bf16 v[118:121], v[226:229], v[194:197], v[118:121]
	v_mfma_f32_16x16x32_bf16 v[118:121], v[230:233], v[198:201], v[118:121]
	v_mfma_f32_16x16x32_bf16 v[114:117], v[234:237], v[194:197], v[114:117]
	v_mfma_f32_16x16x32_bf16 v[114:117], v[238:241], v[198:201], v[114:117]
	v_mfma_f32_16x16x32_bf16 v[102:105], v[226:229], v[202:205], v[102:105]
	v_mfma_f32_16x16x32_bf16 v[102:105], v[230:233], v[206:209], v[102:105]
	v_mfma_f32_16x16x32_bf16 v[98:101], v[234:237], v[202:205], v[98:101]
	v_mfma_f32_16x16x32_bf16 v[98:101], v[238:241], v[206:209], v[98:101]
	v_mfma_f32_16x16x32_bf16 v[86:89], v[226:229], v[210:213], v[86:89]
	v_mfma_f32_16x16x32_bf16 v[86:89], v[230:233], v[214:217], v[86:89]
	v_mfma_f32_16x16x32_bf16 v[82:85], v[234:237], v[210:213], v[82:85]
	v_mfma_f32_16x16x32_bf16 v[82:85], v[238:241], v[214:217], v[82:85]
	v_mfma_f32_16x16x32_bf16 v[70:73], v[226:229], v[218:221], v[70:73]
	v_mfma_f32_16x16x32_bf16 v[70:73], v[230:233], v[222:225], v[70:73]
	v_mfma_f32_16x16x32_bf16 v[66:69], v[234:237], v[218:221], v[66:69]
	s_barrier
	v_mfma_f32_16x16x32_bf16 v[66:69], v[238:241], v[222:225], v[66:69]
	s_setprio 0
	s_mov_b32 m0, s95
	v_lshl_add_u64 v[242:243], vcc, 0, v[136:137]
	ds_read_b128 v[194:197], v166 offset:16384
	ds_read_b128 v[198:201], v166 offset:17408
	ds_read_b128 v[202:205], v166 offset:18432
	ds_read_b128 v[206:209], v166 offset:19456
	ds_read_b128 v[210:213], v166 offset:20480
	ds_read_b128 v[214:217], v166 offset:21504
	ds_read_b128 v[218:221], v166 offset:22528
	ds_read_b128 v[222:225], v166 offset:23552
	global_load_lds_dwordx4 v[242:243], off
	v_lshl_add_u64 v[244:245], vcc, 0, v[132:133]
	s_mov_b32 m0, s96
	s_nop 0
	global_load_lds_dwordx4 v[244:245], off
	s_waitcnt vmcnt(8)
	s_barrier
	s_waitcnt lgkmcnt(0)
	s_setprio 1
	s_waitcnt lgkmcnt(0)
	v_mfma_f32_16x16x32_bf16 v[62:65], v[142:145], v[194:197], v[62:65]
	v_mfma_f32_16x16x32_bf16 v[62:65], v[182:185], v[198:201], v[62:65]
	v_mfma_f32_16x16x32_bf16 v[58:61], v[186:189], v[194:197], v[58:61]
	v_mfma_f32_16x16x32_bf16 v[58:61], v[190:193], v[198:201], v[58:61]
	v_mfma_f32_16x16x32_bf16 v[46:49], v[142:145], v[202:205], v[46:49]
	v_mfma_f32_16x16x32_bf16 v[46:49], v[182:185], v[206:209], v[46:49]
	v_mfma_f32_16x16x32_bf16 v[42:45], v[186:189], v[202:205], v[42:45]
	v_mfma_f32_16x16x32_bf16 v[42:45], v[190:193], v[206:209], v[42:45]
	v_mfma_f32_16x16x32_bf16 v[30:33], v[142:145], v[210:213], v[30:33]
	v_mfma_f32_16x16x32_bf16 v[30:33], v[182:185], v[214:217], v[30:33]
	v_mfma_f32_16x16x32_bf16 v[26:29], v[186:189], v[210:213], v[26:29]
	v_mfma_f32_16x16x32_bf16 v[26:29], v[190:193], v[214:217], v[26:29]
	v_mfma_f32_16x16x32_bf16 v[14:17], v[142:145], v[218:221], v[14:17]
	v_mfma_f32_16x16x32_bf16 v[14:17], v[182:185], v[222:225], v[14:17]
	v_mfma_f32_16x16x32_bf16 v[10:13], v[186:189], v[218:221], v[10:13]
	s_barrier
; #define PG8_STAGE(bufoff, gbase, voff) do { _Pragma("unroll") for (int _i = 0; _i < 2; ++_i) \
;         __builtin_amdgcn_global_load_lds((const unsigned*)((const char*)(gbase) + (voff)[_i]), (LAS unsigned*)(lds + (bufoff) + ldsw + _i * 8192), 16, 0, 0); } while (0)
; #define PG8_LDA(dst, b, h) do { _Pragma("unroll") for (int m = 0; m < 4; ++m) _Pragma("unroll") for (int k = 0; k < 2; ++k) dst[m][k] = *(const LAS bf16x8*)(lds + PG8_SA(b, h) + aoff + m * 2048 + k * 1024); } while (0)
; #define PG8_LDB(dst, b, h) do { _Pragma("unroll") for (int n = 0; n < 2; ++n) _Pragma("unroll") for (int k = 0; k < 2; ++k) dst[n][k] = *(const LAS bf16x8*)(lds + PG8_SB(b, h) + boff + n * 2048 + k * 1024); } while (0)
; #define PG8_MMA(ai, bj, At, Bt) do { __builtin_amdgcn_s_setprio(1); _Pragma("unroll") for (int m = 0; m < 4; ++m) _Pragma("unroll") for (int n = 0; n < 2; ++n) _Pragma("unroll") for (int k = 0; k < 2; ++k) \
;         acc[ai][bj][m][n] = __builtin_amdgcn_mfma_f32_16x16x32_bf16(Bt[n][k], At[m][k], acc[ai][bj][m][n], 0, 0, 0); __builtin_amdgcn_s_setprio(0); } while (0)
; #define PG8_WAIT_V(n) asm volatile("s_waitcnt vmcnt(" #n ")" ::: "memory")
; #define PG8_WAIT_L(n) asm volatile("s_waitcnt lgkmcnt(" #n ")" ::: "memory")
; #define PG8_BAR __builtin_amdgcn_s_barrier()
; #define PG8_SCHED __builtin_amdgcn_sched_barrier(0)
; template <class Epi, class Sched>
; __device__ __forceinline__ void gemm_phase(LAS unsigned char* lds, const Gemm g, const Sched& S, const Epi& E) {
;     ...
;             PG8_STAGE(PG8_SB(0, 1), b2 + hstep, voffB);
;             PG8_WAIT_V(6); PG8_BAR; PG8_MMA(1, 1, At, B1); PG8_BAR;
;             PG8_LDB(B0, 1, 0); PG8_SCHED; PG8_LDA(At, 1, 0); PG8_STAGE(PG8_SA(0, 1), a2 + hstep, voffA);
;             PG8_WAIT_L(8); PG8_BAR; PG8_WAIT_L(0); PG8_MMA(0, 0, At, B0); PG8_BAR; PG8_SCHED;
;             PG8_LDB(B1, 1, 1); PG8_STAGE(PG8_SB(1, 0), b3, voffB);
	v_mfma_f32_16x16x32_bf16 v[10:13], v[190:193], v[222:225], v[10:13]
	s_setprio 0
	s_add_u32 s24, s48, 0x40000
	s_addc_u32 s25, s49, 0
	s_add_i32 s39, s51, s94
	v_lshl_add_u64 v[142:143], s[24:25], 0, v[134:135]
	s_mov_b32 m0, s39
	s_nop 0
	global_load_lds_dwordx4 v[142:143], off
	v_lshl_add_u64 v[250:251], s[24:25], 0, v[130:131]
	s_add_i32 m0, s39, 0x2000
	s_nop 0
	global_load_lds_dwordx4 v[250:251], off
	s_waitcnt vmcnt(6)
	s_barrier
	s_setprio 1
	v_add_u32_e32 v249, 0x18000, v164
	v_mfma_f32_16x16x32_bf16 v[54:57], v[226:229], v[194:197], v[54:57]
	v_mfma_f32_16x16x32_bf16 v[54:57], v[230:233], v[198:201], v[54:57]
	ds_read_b128 v[142:145], v249
	v_mfma_f32_16x16x32_bf16 v[50:53], v[234:237], v[194:197], v[50:53]
	v_mfma_f32_16x16x32_bf16 v[50:53], v[238:241], v[198:201], v[50:53]
	v_mfma_f32_16x16x32_bf16 v[38:41], v[226:229], v[202:205], v[38:41]
	v_mfma_f32_16x16x32_bf16 v[38:41], v[230:233], v[206:209], v[38:41]
	ds_read_b128 v[182:185], v249 offset:1024
	v_mfma_f32_16x16x32_bf16 v[34:37], v[234:237], v[202:205], v[34:37]
	v_mfma_f32_16x16x32_bf16 v[34:37], v[238:241], v[206:209], v[34:37]
	v_mfma_f32_16x16x32_bf16 v[22:25], v[226:229], v[210:213], v[22:25]
	v_mfma_f32_16x16x32_bf16 v[22:25], v[230:233], v[214:217], v[22:25]
	ds_read_b128 v[186:189], v249 offset:2048
	v_mfma_f32_16x16x32_bf16 v[18:21], v[234:237], v[210:213], v[18:21]
	v_mfma_f32_16x16x32_bf16 v[18:21], v[238:241], v[214:217], v[18:21]
	v_mfma_f32_16x16x32_bf16 v[6:9], v[226:229], v[218:221], v[6:9]
	v_mfma_f32_16x16x32_bf16 v[6:9], v[230:233], v[222:225], v[6:9]
	ds_read_b128 v[190:193], v249 offset:3072
	v_mfma_f32_16x16x32_bf16 v[2:5], v[234:237], v[218:221], v[2:5]
	s_barrier
	v_mfma_f32_16x16x32_bf16 v[2:5], v[238:241], v[222:225], v[2:5]
	s_setprio 0
	s_add_i32 s39, 0, 0x18000
	v_add_u32_e32 v167, s39, v164
	s_add_u32 s24, vcc_lo, 0x40000
	s_addc_u32 s25, vcc_hi, 0
	s_mov_b32 m0, s97
	v_lshl_add_u64 v[226:227], s[24:25], 0, v[136:137]
	ds_read_b128 v[194:197], v166 offset:32768
	ds_read_b128 v[198:201], v166 offset:33792
	ds_read_b128 v[202:205], v166 offset:34816
	ds_read_b128 v[206:209], v166 offset:35840
	ds_read_b128 v[210:213], v166 offset:36864
	ds_read_b128 v[214:217], v166 offset:37888
	ds_read_b128 v[218:221], v166 offset:38912
	ds_read_b128 v[222:225], v166 offset:39936
	global_load_lds_dwordx4 v[226:227], off
	v_lshl_add_u64 v[250:251], s[24:25], 0, v[132:133]
	s_mov_b32 m0, s98
	s_nop 0
	global_load_lds_dwordx4 v[250:251], off
	s_waitcnt lgkmcnt(8)
	s_barrier
	s_waitcnt lgkmcnt(0)
	s_setprio 1
	s_waitcnt lgkmcnt(0)
	v_mfma_f32_16x16x32_bf16 v[126:129], v[142:145], v[194:197], v[126:129]
	v_mfma_f32_16x16x32_bf16 v[126:129], v[182:185], v[198:201], v[126:129]
	v_mfma_f32_16x16x32_bf16 v[122:125], v[186:189], v[194:197], v[122:125]
	v_mfma_f32_16x16x32_bf16 v[122:125], v[190:193], v[198:201], v[122:125]
	v_mfma_f32_16x16x32_bf16 v[110:113], v[142:145], v[202:205], v[110:113]
	v_mfma_f32_16x16x32_bf16 v[110:113], v[182:185], v[206:209], v[110:113]
	v_mfma_f32_16x16x32_bf16 v[106:109], v[186:189], v[202:205], v[106:109]
	v_mfma_f32_16x16x32_bf16 v[106:109], v[190:193], v[206:209], v[106:109]
	v_mfma_f32_16x16x32_bf16 v[94:97], v[142:145], v[210:213], v[94:97]
	v_mfma_f32_16x16x32_bf16 v[94:97], v[182:185], v[214:217], v[94:97]
	v_mfma_f32_16x16x32_bf16 v[90:93], v[186:189], v[210:213], v[90:93]
	v_mfma_f32_16x16x32_bf16 v[90:93], v[190:193], v[214:217], v[90:93]
	v_mfma_f32_16x16x32_bf16 v[78:81], v[142:145], v[218:221], v[78:81]
	v_mfma_f32_16x16x32_bf16 v[78:81], v[182:185], v[222:225], v[78:81]
	v_mfma_f32_16x16x32_bf16 v[74:77], v[186:189], v[218:221], v[74:77]
	s_barrier
	v_mfma_f32_16x16x32_bf16 v[74:77], v[190:193], v[222:225], v[74:77]
	s_setprio 0
	s_add_i32 s51, 0, 0x1c000
	s_add_i32 s24, s39, s94
	v_add_u32_e32 v167, s51, v164
	v_lshl_add_u64 v[162:163], v[162:163], 0, s[12:13]
	s_mov_b32 m0, s24
	ds_read_b128 v[226:229], v167
	ds_read_b128 v[230:233], v167 offset:1024
	ds_read_b128 v[234:237], v167 offset:2048
	ds_read_b128 v[238:241], v167 offset:3072
	global_load_lds_dwordx4 v[162:163], off
	v_lshl_add_u64 v[250:251], v[168:169], 0, s[12:13]
	s_add_i32 m0, s24, 0x2000
	s_nop 0
	global_load_lds_dwordx4 v[250:251], off
	s_barrier
; #define PG8_STAGE(bufoff, gbase, voff) do { _Pragma("unroll") for (int _i = 0; _i < 2; ++_i) \
;         __builtin_amdgcn_global_load_lds((const unsigned*)((const char*)(gbase) + (voff)[_i]), (LAS unsigned*)(lds + (bufoff) + ldsw + _i * 8192), 16, 0, 0); } while (0)
; #define PG8_LDA(dst, b, h) do { _Pragma("unroll") for (int m = 0; m < 4; ++m) _Pragma("unroll") for (int k = 0; k < 2; ++k) dst[m][k] = *(const LAS bf16x8*)(lds + PG8_SA(b, h) + aoff + m * 2048 + k * 1024); } while (0)
; #define PG8_MMA(ai, bj, At, Bt) do { __builtin_amdgcn_s_setprio(1); _Pragma("unroll") for (int m = 0; m < 4; ++m) _Pragma("unroll") for (int n = 0; n < 2; ++n) _Pragma("unroll") for (int k = 0; k < 2; ++k) \
;         acc[ai][bj][m][n] = __builtin_amdgcn_mfma_f32_16x16x32_bf16(Bt[n][k], At[m][k], acc[ai][bj][m][n], 0, 0, 0); __builtin_amdgcn_s_setprio(0); } while (0)
; #define PG8_WAIT_V(n) asm volatile("s_waitcnt vmcnt(" #n ")" ::: "memory")
; #define PG8_WAIT_L(n) asm volatile("s_waitcnt lgkmcnt(" #n ")" ::: "memory")
; #define PG8_BAR __builtin_amdgcn_s_barrier()
; #define PG8_SCHED __builtin_amdgcn_sched_barrier(0)
; template <class Epi, class Sched>
; __device__ __forceinline__ void gemm_phase(LAS unsigned char* lds, const Gemm g, const Sched& S, const Epi& E) {
;     ...
;             PG8_BAR; PG8_WAIT_L(0); PG8_MMA(0, 1, At, B1); PG8_BAR;
;             PG8_LDA(At, 1, 1); PG8_STAGE(PG8_SA(1, 0), a3, voffA);
;             PG8_BAR; PG8_WAIT_L(0); PG8_MMA(1, 0, At, B0); PG8_BAR; PG8_SCHED;
;             PG8_STAGE(PG8_SB(1, 1), b3 + hstep, voffB);
;             PG8_WAIT_V(6); PG8_BAR; PG8_MMA(1, 1, At, B1); PG8_BAR;
;         }
;         if (wr == 0) PG8_BAR;
	s_waitcnt lgkmcnt(0)
	s_setprio 1
	s_waitcnt lgkmcnt(0)
	v_mfma_f32_16x16x32_bf16 v[118:121], v[226:229], v[194:197], v[118:121]
	v_mfma_f32_16x16x32_bf16 v[118:121], v[230:233], v[198:201], v[118:121]
	v_mfma_f32_16x16x32_bf16 v[114:117], v[234:237], v[194:197], v[114:117]
	v_mfma_f32_16x16x32_bf16 v[114:117], v[238:241], v[198:201], v[114:117]
	v_mfma_f32_16x16x32_bf16 v[102:105], v[226:229], v[202:205], v[102:105]
	v_mfma_f32_16x16x32_bf16 v[102:105], v[230:233], v[206:209], v[102:105]
	v_mfma_f32_16x16x32_bf16 v[98:101], v[234:237], v[202:205], v[98:101]
	v_mfma_f32_16x16x32_bf16 v[98:101], v[238:241], v[206:209], v[98:101]
	v_mfma_f32_16x16x32_bf16 v[86:89], v[226:229], v[210:213], v[86:89]
	v_mfma_f32_16x16x32_bf16 v[86:89], v[230:233], v[214:217], v[86:89]
	v_mfma_f32_16x16x32_bf16 v[82:85], v[234:237], v[210:213], v[82:85]
	v_mfma_f32_16x16x32_bf16 v[82:85], v[238:241], v[214:217], v[82:85]
	v_mfma_f32_16x16x32_bf16 v[70:73], v[226:229], v[218:221], v[70:73]
	v_mfma_f32_16x16x32_bf16 v[70:73], v[230:233], v[222:225], v[70:73]
	v_mfma_f32_16x16x32_bf16 v[66:69], v[234:237], v[218:221], v[66:69]
	s_barrier
	v_mfma_f32_16x16x32_bf16 v[66:69], v[238:241], v[222:225], v[66:69]
	s_setprio 0
	s_mov_b32 m0, s99
	v_lshl_add_u64 v[162:163], v[242:243], 0, s[12:13]
	ds_read_b128 v[194:197], v166 offset:49152
	ds_read_b128 v[198:201], v166 offset:50176
	ds_read_b128 v[202:205], v166 offset:51200
	ds_read_b128 v[206:209], v166 offset:52224
	ds_read_b128 v[210:213], v166 offset:53248
	ds_read_b128 v[214:217], v166 offset:54272
	ds_read_b128 v[218:221], v166 offset:55296
	ds_read_b128 v[222:225], v166 offset:56320
	global_load_lds_dwordx4 v[162:163], off
	v_lshl_add_u64 v[250:251], v[244:245], 0, s[12:13]
	s_mov_b32 m0, s82
	s_nop 0
	global_load_lds_dwordx4 v[250:251], off
	s_waitcnt vmcnt(8)
	s_barrier
	s_waitcnt lgkmcnt(0)
	s_setprio 1
	s_waitcnt lgkmcnt(0)
	v_mfma_f32_16x16x32_bf16 v[62:65], v[142:145], v[194:197], v[62:65]
	v_mfma_f32_16x16x32_bf16 v[62:65], v[182:185], v[198:201], v[62:65]
	v_mfma_f32_16x16x32_bf16 v[58:61], v[186:189], v[194:197], v[58:61]
	v_mfma_f32_16x16x32_bf16 v[58:61], v[190:193], v[198:201], v[58:61]
	v_mfma_f32_16x16x32_bf16 v[46:49], v[142:145], v[202:205], v[46:49]
	v_mfma_f32_16x16x32_bf16 v[46:49], v[182:185], v[206:209], v[46:49]
	v_mfma_f32_16x16x32_bf16 v[42:45], v[186:189], v[202:205], v[42:45]
	v_mfma_f32_16x16x32_bf16 v[42:45], v[190:193], v[206:209], v[42:45]
	v_mfma_f32_16x16x32_bf16 v[30:33], v[142:145], v[210:213], v[30:33]
	v_mfma_f32_16x16x32_bf16 v[30:33], v[182:185], v[214:217], v[30:33]
	v_mfma_f32_16x16x32_bf16 v[26:29], v[186:189], v[210:213], v[26:29]
	v_mfma_f32_16x16x32_bf16 v[26:29], v[190:193], v[214:217], v[26:29]
	v_mfma_f32_16x16x32_bf16 v[14:17], v[142:145], v[218:221], v[14:17]
	v_mfma_f32_16x16x32_bf16 v[14:17], v[182:185], v[222:225], v[14:17]
	v_mfma_f32_16x16x32_bf16 v[10:13], v[186:189], v[218:221], v[10:13]
	s_barrier
	v_mfma_f32_16x16x32_bf16 v[10:13], v[190:193], v[222:225], v[10:13]
	s_setprio 0
	s_add_u32 s24, s48, 0x40080
	s_addc_u32 s25, s49, 0
	s_add_i32 s39, s51, s94
	v_lshl_add_u64 v[142:143], s[24:25], 0, v[134:135]
	s_mov_b32 m0, s39
	s_nop 0
	global_load_lds_dwordx4 v[142:143], off
	v_lshl_add_u64 v[250:251], s[24:25], 0, v[130:131]
	s_add_i32 m0, s39, 0x2000
	s_nop 0
	global_load_lds_dwordx4 v[250:251], off
	s_waitcnt vmcnt(6)
	s_barrier
	s_setprio 1
	v_add_u32_e32 v249, 0x10000, v164
	v_mfma_f32_16x16x32_bf16 v[54:57], v[226:229], v[194:197], v[54:57]
	v_mfma_f32_16x16x32_bf16 v[54:57], v[230:233], v[198:201], v[54:57]
	ds_read_b128 v[142:145], v249
	v_mfma_f32_16x16x32_bf16 v[50:53], v[234:237], v[194:197], v[50:53]
	v_mfma_f32_16x16x32_bf16 v[50:53], v[238:241], v[198:201], v[50:53]
	v_mfma_f32_16x16x32_bf16 v[38:41], v[226:229], v[202:205], v[38:41]
	v_mfma_f32_16x16x32_bf16 v[38:41], v[230:233], v[206:209], v[38:41]
	ds_read_b128 v[182:185], v249 offset:1024
	v_mfma_f32_16x16x32_bf16 v[34:37], v[234:237], v[202:205], v[34:37]
	v_mfma_f32_16x16x32_bf16 v[34:37], v[238:241], v[206:209], v[34:37]
	v_mfma_f32_16x16x32_bf16 v[22:25], v[226:229], v[210:213], v[22:25]
	v_mfma_f32_16x16x32_bf16 v[22:25], v[230:233], v[214:217], v[22:25]
	ds_read_b128 v[186:189], v249 offset:2048
	v_mfma_f32_16x16x32_bf16 v[18:21], v[234:237], v[210:213], v[18:21]
	v_mfma_f32_16x16x32_bf16 v[18:21], v[238:241], v[214:217], v[18:21]
	v_mfma_f32_16x16x32_bf16 v[6:9], v[226:229], v[218:221], v[6:9]
	v_mfma_f32_16x16x32_bf16 v[6:9], v[230:233], v[222:225], v[6:9]
	ds_read_b128 v[190:193], v249 offset:3072
	v_mfma_f32_16x16x32_bf16 v[2:5], v[234:237], v[218:221], v[2:5]
	s_barrier
	v_mfma_f32_16x16x32_bf16 v[2:5], v[238:241], v[222:225], v[2:5]
	s_setprio 0
	s_add_i32 s38, s38, 2
	s_add_u32 s35, s35, 0x100
	s_addc_u32 s50, s50, 0
	s_add_u32 s0, s0, 0x100
	s_addc_u32 s1, s1, 0
	s_cmp_gt_u32 s38, 13
	s_cbranch_scc0 .LBB0_557
	s_waitcnt lgkmcnt(0)
	s_and_b64 vcc, exec, s[42:43]
	s_cbranch_vccz .LBB0_560
	s_barrier

; #define PG8_STAGE(bufoff, gbase, voff) do { _Pragma("unroll") for (int _i = 0; _i < 2; ++_i) \
;         __builtin_amdgcn_global_load_lds((const unsigned*)((const char*)(gbase) + (voff)[_i]), (LAS unsigned*)(lds + (bufoff) + ldsw + _i * 8192), 16, 0, 0); } while (0)
; #define PG8_LDA(dst, b, h) do { _Pragma("unroll") for (int m = 0; m < 4; ++m) _Pragma("unroll") for (int k = 0; k < 2; ++k) dst[m][k] = *(const LAS bf16x8*)(lds + PG8_SA(b, h) + aoff + m * 2048 + k * 1024); } while (0)
; #define PG8_LDB(dst, b, h) do { _Pragma("unroll") for (int n = 0; n < 2; ++n) _Pragma("unroll") for (int k = 0; k < 2; ++k) dst[n][k] = *(const LAS bf16x8*)(lds + PG8_SB(b, h) + boff + n * 2048 + k * 1024); } while (0)
; #define PG8_MMA(ai, bj, At, Bt) do { __builtin_amdgcn_s_setprio(1); _Pragma("unroll") for (int m = 0; m < 4; ++m) _Pragma("unroll") for (int n = 0; n < 2; ++n) _Pragma("unroll") for (int k = 0; k < 2; ++k) \
;         acc[ai][bj][m][n] = __builtin_amdgcn_mfma_f32_16x16x32_bf16(Bt[n][k], At[m][k], acc[ai][bj][m][n], 0, 0, 0); __builtin_amdgcn_s_setprio(0); } while (0)
; #define PG8_WAIT_L(n) asm volatile("s_waitcnt lgkmcnt(" #n ")" ::: "memory")
; #define PG8_BAR __builtin_amdgcn_s_barrier()
; #define PG8_SCHED __builtin_amdgcn_sched_barrier(0)
; template <class Epi, class Sched>
; __device__ __forceinline__ void gemm_phase(LAS unsigned char* lds, const Gemm g, const Sched& S, const Epi& E) {
;     ...
;         for (int t = 0; t < nt; t += 2) {
;             const bool last = (t == nt - 2);
;             const char* a1 = cA + (size_t)(t + 1) * kstep;
;             const char* a2 = last ? nA : cA + (size_t)(t + 2) * kstep; const char* b2 = last ? nB : cB + (size_t)(t + 2) * kstep;
;             const char* a3 = a2 + kstep; const char* b3 = b2 + kstep;
;             PG8_LDB(B0, 0, 0); PG8_SCHED; PG8_LDA(At, 0, 0); PG8_STAGE(PG8_SA(1, 1), a1 + hstep, voffA);
;             PG8_WAIT_L(8); PG8_BAR; PG8_WAIT_L(0); PG8_MMA(0, 0, At, B0); PG8_BAR; PG8_SCHED;
;             PG8_LDB(B1, 0, 1); PG8_STAGE(PG8_SB(0, 0), b2, voffB);
;             PG8_BAR; PG8_WAIT_L(0); PG8_MMA(0, 1, At, B1); PG8_BAR;
;             PG8_LDA(At, 0, 1); PG8_STAGE(PG8_SA(0, 0), a2, voffA);
;             PG8_BAR; PG8_WAIT_L(0); PG8_MMA(1, 0, At, B0); PG8_BAR; PG8_SCHED;
.LBB0_627:
	s_add_u32 s24, s0, 0xfff00080
	s_addc_u32 s25, s1, -1
	s_add_i32 s51, 0, 0x10000
	v_add_u32_e32 v142, s51, v144
	s_cmp_eq_u32 s98, 60
	s_cselect_b32 s77, s47, s25
	s_cselect_b32 s76, s46, s24
	s_cselect_b32 s49, s43, s50
	s_cselect_b32 s48, s45, s35
	v_lshl_add_u64 v[142:143], s[0:1], 0, v[140:141]
	s_add_i32 m0, s86, 0xc000
	ds_read_b128 v[194:197], v162
	ds_read_b128 v[198:201], v162 offset:1024
	ds_read_b128 v[202:205], v162 offset:2048
	ds_read_b128 v[206:209], v162 offset:3072
	ds_read_b128 v[210:213], v162 offset:4096
	ds_read_b128 v[214:217], v162 offset:5120
	ds_read_b128 v[218:221], v162 offset:6144
	ds_read_b128 v[222:225], v162 offset:7168
	global_load_lds_dwordx4 v[142:143], off
	v_lshl_add_u64 v[250:251], s[0:1], 0, v[138:139]
	s_add_i32 m0, s86, 0xe000
	s_nop 0
	global_load_lds_dwordx4 v[250:251], off
	s_waitcnt lgkmcnt(8)
	s_barrier
	s_waitcnt lgkmcnt(0)
	s_setprio 1
	s_waitcnt lgkmcnt(0)
	v_mfma_f32_16x16x32_bf16 v[126:129], v[164:167], v[194:197], v[126:129]
	v_mfma_f32_16x16x32_bf16 v[126:129], v[182:185], v[198:201], v[126:129]
	v_mfma_f32_16x16x32_bf16 v[122:125], v[186:189], v[194:197], v[122:125]
	v_mfma_f32_16x16x32_bf16 v[122:125], v[190:193], v[198:201], v[122:125]
	v_mfma_f32_16x16x32_bf16 v[118:121], v[164:167], v[202:205], v[118:121]
	v_mfma_f32_16x16x32_bf16 v[118:121], v[182:185], v[206:209], v[118:121]
	v_mfma_f32_16x16x32_bf16 v[110:113], v[186:189], v[202:205], v[110:113]
	v_mfma_f32_16x16x32_bf16 v[110:113], v[190:193], v[206:209], v[110:113]
	v_mfma_f32_16x16x32_bf16 v[102:105], v[164:167], v[210:213], v[102:105]
	v_mfma_f32_16x16x32_bf16 v[102:105], v[182:185], v[214:217], v[102:105]
	v_mfma_f32_16x16x32_bf16 v[94:97], v[186:189], v[210:213], v[94:97]
	v_mfma_f32_16x16x32_bf16 v[94:97], v[190:193], v[214:217], v[94:97]
	v_mfma_f32_16x16x32_bf16 v[86:89], v[164:167], v[218:221], v[86:89]
	v_mfma_f32_16x16x32_bf16 v[86:89], v[182:185], v[222:225], v[86:89]
	v_mfma_f32_16x16x32_bf16 v[78:81], v[186:189], v[218:221], v[78:81]
	s_barrier
	v_mfma_f32_16x16x32_bf16 v[78:81], v[190:193], v[222:225], v[78:81]
	s_setprio 0
	s_add_i32 s99, 0, 0x14000
	v_add_u32_e32 v142, s99, v144
	s_add_i32 s24, s51, s83
	ds_read_b128 v[226:229], v142
	ds_read_b128 v[230:233], v142 offset:1024
	ds_read_b128 v[234:237], v142 offset:2048
	ds_read_b128 v[238:241], v142 offset:3072
	v_lshl_add_u64 v[142:143], s[48:49], 0, v[134:135]
	s_mov_b32 m0, s24
	v_lshl_add_u64 v[168:169], s[48:49], 0, v[130:131]
	global_load_lds_dwordx4 v[142:143], off
	s_add_i32 m0, s24, 0x2000
	s_nop 0
	global_load_lds_dwordx4 v[168:169], off
	s_barrier
	s_waitcnt lgkmcnt(0)
	s_setprio 1
	s_waitcnt lgkmcnt(0)
	v_mfma_f32_16x16x32_bf16 v[114:117], v[226:229], v[194:197], v[114:117]
	v_mfma_f32_16x16x32_bf16 v[114:117], v[230:233], v[198:201], v[114:117]
	v_mfma_f32_16x16x32_bf16 v[106:109], v[234:237], v[194:197], v[106:109]
	v_mfma_f32_16x16x32_bf16 v[106:109], v[238:241], v[198:201], v[106:109]
	v_mfma_f32_16x16x32_bf16 v[98:101], v[226:229], v[202:205], v[98:101]
	v_mfma_f32_16x16x32_bf16 v[98:101], v[230:233], v[206:209], v[98:101]
	v_mfma_f32_16x16x32_bf16 v[90:93], v[234:237], v[202:205], v[90:93]
	v_mfma_f32_16x16x32_bf16 v[90:93], v[238:241], v[206:209], v[90:93]
	v_mfma_f32_16x16x32_bf16 v[82:85], v[226:229], v[210:213], v[82:85]
	v_mfma_f32_16x16x32_bf16 v[82:85], v[230:233], v[214:217], v[82:85]
	v_mfma_f32_16x16x32_bf16 v[74:77], v[234:237], v[210:213], v[74:77]
	v_mfma_f32_16x16x32_bf16 v[74:77], v[238:241], v[214:217], v[74:77]
	v_mfma_f32_16x16x32_bf16 v[70:73], v[226:229], v[218:221], v[70:73]
	v_mfma_f32_16x16x32_bf16 v[70:73], v[230:233], v[222:225], v[70:73]
	v_mfma_f32_16x16x32_bf16 v[66:69], v[234:237], v[218:221], v[66:69]
	s_barrier
	v_mfma_f32_16x16x32_bf16 v[66:69], v[238:241], v[222:225], v[66:69]
	s_setprio 0
	s_mov_b32 m0, s86
	v_lshl_add_u64 v[242:243], s[76:77], 0, v[136:137]
	ds_read_b128 v[194:197], v162 offset:16384
	ds_read_b128 v[198:201], v162 offset:17408
	ds_read_b128 v[202:205], v162 offset:18432
	ds_read_b128 v[206:209], v162 offset:19456
	ds_read_b128 v[210:213], v162 offset:20480
	ds_read_b128 v[214:217], v162 offset:21504
	ds_read_b128 v[218:221], v162 offset:22528
	ds_read_b128 v[222:225], v162 offset:23552
	global_load_lds_dwordx4 v[242:243], off
	v_lshl_add_u64 v[244:245], s[76:77], 0, v[132:133]
	s_mov_b32 m0, s92
	s_nop 0
	global_load_lds_dwordx4 v[244:245], off
	s_waitcnt vmcnt(8)
	s_barrier
	s_waitcnt lgkmcnt(0)
	s_setprio 1
	s_waitcnt lgkmcnt(0)
	v_mfma_f32_16x16x32_bf16 v[62:65], v[164:167], v[194:197], v[62:65]
	v_mfma_f32_16x16x32_bf16 v[62:65], v[182:185], v[198:201], v[62:65]
	v_mfma_f32_16x16x32_bf16 v[58:61], v[186:189], v[194:197], v[58:61]
	v_mfma_f32_16x16x32_bf16 v[58:61], v[190:193], v[198:201], v[58:61]
	v_mfma_f32_16x16x32_bf16 v[54:57], v[164:167], v[202:205], v[54:57]
	v_mfma_f32_16x16x32_bf16 v[54:57], v[182:185], v[206:209], v[54:57]
	v_mfma_f32_16x16x32_bf16 v[46:49], v[186:189], v[202:205], v[46:49]
	v_mfma_f32_16x16x32_bf16 v[46:49], v[190:193], v[206:209], v[46:49]
	v_mfma_f32_16x16x32_bf16 v[38:41], v[164:167], v[210:213], v[38:41]
	v_mfma_f32_16x16x32_bf16 v[38:41], v[182:185], v[214:217], v[38:41]
	v_mfma_f32_16x16x32_bf16 v[30:33], v[186:189], v[210:213], v[30:33]
	v_mfma_f32_16x16x32_bf16 v[30:33], v[190:193], v[214:217], v[30:33]
	v_mfma_f32_16x16x32_bf16 v[22:25], v[164:167], v[218:221], v[22:25]
	v_mfma_f32_16x16x32_bf16 v[22:25], v[182:185], v[222:225], v[22:25]
	v_mfma_f32_16x16x32_bf16 v[14:17], v[186:189], v[218:221], v[14:17]
	s_barrier
; #define PG8_STAGE(bufoff, gbase, voff) do { _Pragma("unroll") for (int _i = 0; _i < 2; ++_i) \
;         __builtin_amdgcn_global_load_lds((const unsigned*)((const char*)(gbase) + (voff)[_i]), (LAS unsigned*)(lds + (bufoff) + ldsw + _i * 8192), 16, 0, 0); } while (0)
; #define PG8_LDA(dst, b, h) do { _Pragma("unroll") for (int m = 0; m < 4; ++m) _Pragma("unroll") for (int k = 0; k < 2; ++k) dst[m][k] = *(const LAS bf16x8*)(lds + PG8_SA(b, h) + aoff + m * 2048 + k * 1024); } while (0)
; #define PG8_LDB(dst, b, h) do { _Pragma("unroll") for (int n = 0; n < 2; ++n) _Pragma("unroll") for (int k = 0; k < 2; ++k) dst[n][k] = *(const LAS bf16x8*)(lds + PG8_SB(b, h) + boff + n * 2048 + k * 1024); } while (0)
; #define PG8_MMA(ai, bj, At, Bt) do { __builtin_amdgcn_s_setprio(1); _Pragma("unroll") for (int m = 0; m < 4; ++m) _Pragma("unroll") for (int n = 0; n < 2; ++n) _Pragma("unroll") for (int k = 0; k < 2; ++k) \
;         acc[ai][bj][m][n] = __builtin_amdgcn_mfma_f32_16x16x32_bf16(Bt[n][k], At[m][k], acc[ai][bj][m][n], 0, 0, 0); __builtin_amdgcn_s_setprio(0); } while (0)
; #define PG8_WAIT_V(n) asm volatile("s_waitcnt vmcnt(" #n ")" ::: "memory")
; #define PG8_WAIT_L(n) asm volatile("s_waitcnt lgkmcnt(" #n ")" ::: "memory")
; #define PG8_BAR __builtin_amdgcn_s_barrier()
; #define PG8_SCHED __builtin_amdgcn_sched_barrier(0)
; template <class Epi, class Sched>
; __device__ __forceinline__ void gemm_phase(LAS unsigned char* lds, const Gemm g, const Sched& S, const Epi& E) {
;     ...
;             PG8_STAGE(PG8_SB(0, 1), b2 + hstep, voffB);
;             PG8_WAIT_V(6); PG8_BAR; PG8_MMA(1, 1, At, B1); PG8_BAR;
;             PG8_LDB(B0, 1, 0); PG8_SCHED; PG8_LDA(At, 1, 0); PG8_STAGE(PG8_SA(0, 1), a2 + hstep, voffA);
;             PG8_WAIT_L(8); PG8_BAR; PG8_WAIT_L(0); PG8_MMA(0, 0, At, B0); PG8_BAR; PG8_SCHED;
;             PG8_LDB(B1, 1, 1); PG8_STAGE(PG8_SB(1, 0), b3, voffB);
	v_mfma_f32_16x16x32_bf16 v[14:17], v[190:193], v[222:225], v[14:17]
	s_setprio 0
	s_add_u32 s24, s48, 0x100000
	s_addc_u32 s25, s49, 0
	s_add_i32 s51, s99, s83
	v_lshl_add_u64 v[164:165], s[24:25], 0, v[134:135]
	s_mov_b32 m0, s51
	s_nop 0
	global_load_lds_dwordx4 v[164:165], off
	v_lshl_add_u64 v[250:251], s[24:25], 0, v[130:131]
	s_add_i32 m0, s51, 0x2000
	s_nop 0
	global_load_lds_dwordx4 v[250:251], off
	s_waitcnt vmcnt(6)
	s_barrier
	s_setprio 1
	v_add_u32_e32 v249, 0x18000, v144
	v_mfma_f32_16x16x32_bf16 v[50:53], v[226:229], v[194:197], v[50:53]
	v_mfma_f32_16x16x32_bf16 v[50:53], v[230:233], v[198:201], v[50:53]
	ds_read_b128 v[164:167], v249
	v_mfma_f32_16x16x32_bf16 v[42:45], v[234:237], v[194:197], v[42:45]
	v_mfma_f32_16x16x32_bf16 v[42:45], v[238:241], v[198:201], v[42:45]
	v_mfma_f32_16x16x32_bf16 v[34:37], v[226:229], v[202:205], v[34:37]
	v_mfma_f32_16x16x32_bf16 v[34:37], v[230:233], v[206:209], v[34:37]
	ds_read_b128 v[182:185], v249 offset:1024
	v_mfma_f32_16x16x32_bf16 v[26:29], v[234:237], v[202:205], v[26:29]
	v_mfma_f32_16x16x32_bf16 v[26:29], v[238:241], v[206:209], v[26:29]
	v_mfma_f32_16x16x32_bf16 v[18:21], v[226:229], v[210:213], v[18:21]
	v_mfma_f32_16x16x32_bf16 v[18:21], v[230:233], v[214:217], v[18:21]
	ds_read_b128 v[186:189], v249 offset:2048
	v_mfma_f32_16x16x32_bf16 v[10:13], v[234:237], v[210:213], v[10:13]
	v_mfma_f32_16x16x32_bf16 v[10:13], v[238:241], v[214:217], v[10:13]
	v_mfma_f32_16x16x32_bf16 v[6:9], v[226:229], v[218:221], v[6:9]
	v_mfma_f32_16x16x32_bf16 v[6:9], v[230:233], v[222:225], v[6:9]
	ds_read_b128 v[190:193], v249 offset:3072
	v_mfma_f32_16x16x32_bf16 v[2:5], v[234:237], v[218:221], v[2:5]
	s_barrier
	v_mfma_f32_16x16x32_bf16 v[2:5], v[238:241], v[222:225], v[2:5]
	s_setprio 0
	s_add_i32 s51, 0, 0x18000
	v_add_u32_e32 v163, s51, v144
	s_add_u32 s24, s76, 0x100000
	s_addc_u32 s25, s77, 0
	s_mov_b32 m0, s93
	v_lshl_add_u64 v[226:227], s[24:25], 0, v[136:137]
	ds_read_b128 v[194:197], v162 offset:32768
	ds_read_b128 v[198:201], v162 offset:33792
	ds_read_b128 v[202:205], v162 offset:34816
	ds_read_b128 v[206:209], v162 offset:35840
	ds_read_b128 v[210:213], v162 offset:36864
	ds_read_b128 v[214:217], v162 offset:37888
	ds_read_b128 v[218:221], v162 offset:38912
	ds_read_b128 v[222:225], v162 offset:39936
	global_load_lds_dwordx4 v[226:227], off
	v_lshl_add_u64 v[250:251], s[24:25], 0, v[132:133]
	s_mov_b32 m0, s94
	s_nop 0
	global_load_lds_dwordx4 v[250:251], off
	s_waitcnt lgkmcnt(8)
	s_barrier
	s_waitcnt lgkmcnt(0)
	s_setprio 1
	s_waitcnt lgkmcnt(0)
	v_mfma_f32_16x16x32_bf16 v[126:129], v[164:167], v[194:197], v[126:129]
	v_mfma_f32_16x16x32_bf16 v[126:129], v[182:185], v[198:201], v[126:129]
	v_mfma_f32_16x16x32_bf16 v[122:125], v[186:189], v[194:197], v[122:125]
	v_mfma_f32_16x16x32_bf16 v[122:125], v[190:193], v[198:201], v[122:125]
	v_mfma_f32_16x16x32_bf16 v[118:121], v[164:167], v[202:205], v[118:121]
	v_mfma_f32_16x16x32_bf16 v[118:121], v[182:185], v[206:209], v[118:121]
	v_mfma_f32_16x16x32_bf16 v[110:113], v[186:189], v[202:205], v[110:113]
	v_mfma_f32_16x16x32_bf16 v[110:113], v[190:193], v[206:209], v[110:113]
	v_mfma_f32_16x16x32_bf16 v[102:105], v[164:167], v[210:213], v[102:105]
	v_mfma_f32_16x16x32_bf16 v[102:105], v[182:185], v[214:217], v[102:105]
	v_mfma_f32_16x16x32_bf16 v[94:97], v[186:189], v[210:213], v[94:97]
	v_mfma_f32_16x16x32_bf16 v[94:97], v[190:193], v[214:217], v[94:97]
	v_mfma_f32_16x16x32_bf16 v[86:89], v[164:167], v[218:221], v[86:89]
	v_mfma_f32_16x16x32_bf16 v[86:89], v[182:185], v[222:225], v[86:89]
	v_mfma_f32_16x16x32_bf16 v[78:81], v[186:189], v[218:221], v[78:81]
	s_barrier
	v_mfma_f32_16x16x32_bf16 v[78:81], v[190:193], v[222:225], v[78:81]
	s_setprio 0
	s_add_i32 s76, 0, 0x1c000
	s_add_i32 s24, s51, s83
	v_add_u32_e32 v163, s76, v144
	v_lshl_add_u64 v[142:143], v[142:143], 0, s[12:13]
	s_mov_b32 m0, s24
	ds_read_b128 v[226:229], v163
	ds_read_b128 v[230:233], v163 offset:1024
	ds_read_b128 v[234:237], v163 offset:2048
	ds_read_b128 v[238:241], v163 offset:3072
	global_load_lds_dwordx4 v[142:143], off
	v_lshl_add_u64 v[250:251], v[168:169], 0, s[12:13]
	s_add_i32 m0, s24, 0x2000
	s_nop 0
	global_load_lds_dwordx4 v[250:251], off
	s_barrier
; #define PG8_STAGE(bufoff, gbase, voff) do { _Pragma("unroll") for (int _i = 0; _i < 2; ++_i) \
;         __builtin_amdgcn_global_load_lds((const unsigned*)((const char*)(gbase) + (voff)[_i]), (LAS unsigned*)(lds + (bufoff) + ldsw + _i * 8192), 16, 0, 0); } while (0)
; #define PG8_LDA(dst, b, h) do { _Pragma("unroll") for (int m = 0; m < 4; ++m) _Pragma("unroll") for (int k = 0; k < 2; ++k) dst[m][k] = *(const LAS bf16x8*)(lds + PG8_SA(b, h) + aoff + m * 2048 + k * 1024); } while (0)
; #define PG8_MMA(ai, bj, At, Bt) do { __builtin_amdgcn_s_setprio(1); _Pragma("unroll") for (int m = 0; m < 4; ++m) _Pragma("unroll") for (int n = 0; n < 2; ++n) _Pragma("unroll") for (int k = 0; k < 2; ++k) \
;         acc[ai][bj][m][n] = __builtin_amdgcn_mfma_f32_16x16x32_bf16(Bt[n][k], At[m][k], acc[ai][bj][m][n], 0, 0, 0); __builtin_amdgcn_s_setprio(0); } while (0)
; #define PG8_WAIT_V(n) asm volatile("s_waitcnt vmcnt(" #n ")" ::: "memory")
; #define PG8_WAIT_L(n) asm volatile("s_waitcnt lgkmcnt(" #n ")" ::: "memory")
; #define PG8_BAR __builtin_amdgcn_s_barrier()
; #define PG8_SCHED __builtin_amdgcn_sched_barrier(0)
; template <class Epi, class Sched>
; __device__ __forceinline__ void gemm_phase(LAS unsigned char* lds, const Gemm g, const Sched& S, const Epi& E) {
;     ...
;             PG8_BAR; PG8_WAIT_L(0); PG8_MMA(0, 1, At, B1); PG8_BAR;
;             PG8_LDA(At, 1, 1); PG8_STAGE(PG8_SA(1, 0), a3, voffA);
;             PG8_BAR; PG8_WAIT_L(0); PG8_MMA(1, 0, At, B0); PG8_BAR; PG8_SCHED;
;             PG8_STAGE(PG8_SB(1, 1), b3 + hstep, voffB);
;             PG8_WAIT_V(6); PG8_BAR; PG8_MMA(1, 1, At, B1); PG8_BAR;
;         }
;         if (wr == 0) PG8_BAR;
	s_waitcnt lgkmcnt(0)
	s_setprio 1
	s_waitcnt lgkmcnt(0)
	v_mfma_f32_16x16x32_bf16 v[114:117], v[226:229], v[194:197], v[114:117]
	v_mfma_f32_16x16x32_bf16 v[114:117], v[230:233], v[198:201], v[114:117]
	v_mfma_f32_16x16x32_bf16 v[106:109], v[234:237], v[194:197], v[106:109]
	v_mfma_f32_16x16x32_bf16 v[106:109], v[238:241], v[198:201], v[106:109]
	v_mfma_f32_16x16x32_bf16 v[98:101], v[226:229], v[202:205], v[98:101]
	v_mfma_f32_16x16x32_bf16 v[98:101], v[230:233], v[206:209], v[98:101]
	v_mfma_f32_16x16x32_bf16 v[90:93], v[234:237], v[202:205], v[90:93]
	v_mfma_f32_16x16x32_bf16 v[90:93], v[238:241], v[206:209], v[90:93]
	v_mfma_f32_16x16x32_bf16 v[82:85], v[226:229], v[210:213], v[82:85]
	v_mfma_f32_16x16x32_bf16 v[82:85], v[230:233], v[214:217], v[82:85]
	v_mfma_f32_16x16x32_bf16 v[74:77], v[234:237], v[210:213], v[74:77]
	v_mfma_f32_16x16x32_bf16 v[74:77], v[238:241], v[214:217], v[74:77]
	v_mfma_f32_16x16x32_bf16 v[70:73], v[226:229], v[218:221], v[70:73]
	v_mfma_f32_16x16x32_bf16 v[70:73], v[230:233], v[222:225], v[70:73]
	v_mfma_f32_16x16x32_bf16 v[66:69], v[234:237], v[218:221], v[66:69]
	s_barrier
	v_mfma_f32_16x16x32_bf16 v[66:69], v[238:241], v[222:225], v[66:69]
	s_setprio 0
	s_mov_b32 m0, s95
	v_lshl_add_u64 v[142:143], v[242:243], 0, s[12:13]
	ds_read_b128 v[194:197], v162 offset:49152
	ds_read_b128 v[198:201], v162 offset:50176
	ds_read_b128 v[202:205], v162 offset:51200
	ds_read_b128 v[206:209], v162 offset:52224
	ds_read_b128 v[210:213], v162 offset:53248
	ds_read_b128 v[214:217], v162 offset:54272
	ds_read_b128 v[218:221], v162 offset:55296
	ds_read_b128 v[222:225], v162 offset:56320
	global_load_lds_dwordx4 v[142:143], off
	v_lshl_add_u64 v[250:251], v[244:245], 0, s[12:13]
	s_mov_b32 m0, s96
	s_nop 0
	global_load_lds_dwordx4 v[250:251], off
	s_waitcnt vmcnt(8)
	s_barrier
	s_waitcnt lgkmcnt(0)
	s_setprio 1
	s_waitcnt lgkmcnt(0)
	v_mfma_f32_16x16x32_bf16 v[62:65], v[164:167], v[194:197], v[62:65]
	v_mfma_f32_16x16x32_bf16 v[62:65], v[182:185], v[198:201], v[62:65]
	v_mfma_f32_16x16x32_bf16 v[58:61], v[186:189], v[194:197], v[58:61]
	v_mfma_f32_16x16x32_bf16 v[58:61], v[190:193], v[198:201], v[58:61]
	v_mfma_f32_16x16x32_bf16 v[54:57], v[164:167], v[202:205], v[54:57]
	v_mfma_f32_16x16x32_bf16 v[54:57], v[182:185], v[206:209], v[54:57]
	v_mfma_f32_16x16x32_bf16 v[46:49], v[186:189], v[202:205], v[46:49]
	v_mfma_f32_16x16x32_bf16 v[46:49], v[190:193], v[206:209], v[46:49]
	v_mfma_f32_16x16x32_bf16 v[38:41], v[164:167], v[210:213], v[38:41]
	v_mfma_f32_16x16x32_bf16 v[38:41], v[182:185], v[214:217], v[38:41]
	v_mfma_f32_16x16x32_bf16 v[30:33], v[186:189], v[210:213], v[30:33]
	v_mfma_f32_16x16x32_bf16 v[30:33], v[190:193], v[214:217], v[30:33]
	v_mfma_f32_16x16x32_bf16 v[22:25], v[164:167], v[218:221], v[22:25]
	v_mfma_f32_16x16x32_bf16 v[22:25], v[182:185], v[222:225], v[22:25]
	v_mfma_f32_16x16x32_bf16 v[14:17], v[186:189], v[218:221], v[14:17]
	s_barrier
	v_mfma_f32_16x16x32_bf16 v[14:17], v[190:193], v[222:225], v[14:17]
	s_setprio 0
	s_add_u32 s24, s48, 0x100080
	s_addc_u32 s25, s49, 0
	s_add_i32 s48, s76, s83
	v_lshl_add_u64 v[142:143], s[24:25], 0, v[134:135]
	s_mov_b32 m0, s48
	s_nop 0
	global_load_lds_dwordx4 v[142:143], off
	v_lshl_add_u64 v[250:251], s[24:25], 0, v[130:131]
	s_add_i32 m0, s48, 0x2000
	s_nop 0
	global_load_lds_dwordx4 v[250:251], off
	s_waitcnt vmcnt(6)
	s_barrier
	s_setprio 1
	v_add_u32_e32 v249, 0x10000, v144
	v_mfma_f32_16x16x32_bf16 v[50:53], v[226:229], v[194:197], v[50:53]
	v_mfma_f32_16x16x32_bf16 v[50:53], v[230:233], v[198:201], v[50:53]
	ds_read_b128 v[164:167], v249
	v_mfma_f32_16x16x32_bf16 v[42:45], v[234:237], v[194:197], v[42:45]
	v_mfma_f32_16x16x32_bf16 v[42:45], v[238:241], v[198:201], v[42:45]
	v_mfma_f32_16x16x32_bf16 v[34:37], v[226:229], v[202:205], v[34:37]
	v_mfma_f32_16x16x32_bf16 v[34:37], v[230:233], v[206:209], v[34:37]
	ds_read_b128 v[182:185], v249 offset:1024
	v_mfma_f32_16x16x32_bf16 v[26:29], v[234:237], v[202:205], v[26:29]
	v_mfma_f32_16x16x32_bf16 v[26:29], v[238:241], v[206:209], v[26:29]
	v_mfma_f32_16x16x32_bf16 v[18:21], v[226:229], v[210:213], v[18:21]
	v_mfma_f32_16x16x32_bf16 v[18:21], v[230:233], v[214:217], v[18:21]
	ds_read_b128 v[186:189], v249 offset:2048
	v_mfma_f32_16x16x32_bf16 v[10:13], v[234:237], v[210:213], v[10:13]
	v_mfma_f32_16x16x32_bf16 v[10:13], v[238:241], v[214:217], v[10:13]
	v_mfma_f32_16x16x32_bf16 v[6:9], v[226:229], v[218:221], v[6:9]
	v_mfma_f32_16x16x32_bf16 v[6:9], v[230:233], v[222:225], v[6:9]
	ds_read_b128 v[190:193], v249 offset:3072
	v_mfma_f32_16x16x32_bf16 v[2:5], v[234:237], v[218:221], v[2:5]
	s_barrier
	v_mfma_f32_16x16x32_bf16 v[2:5], v[238:241], v[222:225], v[2:5]
	s_setprio 0
	s_add_i32 s98, s98, 2
	s_add_u32 s35, s35, 0x100
	s_addc_u32 s50, s50, 0
	s_add_u32 s0, s0, 0x100
	s_addc_u32 s1, s1, 0
	s_cmp_gt_u32 s98, 61
	s_cbranch_scc0 .LBB0_627
	s_waitcnt lgkmcnt(0)
	s_and_b64 vcc, exec, s[40:41]
	s_cbranch_vccz .LBB0_630
	s_barrier
